# FFN-gate epilogue: removed 161 dead zero-initialisations of row_ror DPP move destinations
# baseline (speedup 1.0000x reference)
; #define DPP_UP(v) __int_as_float(__builtin_amdgcn_update_dpp(0, __float_as_int(v), 0x121, 0xf, 0xf, false))
; #define DPP_DN(v) __int_as_float(__builtin_amdgcn_update_dpp(0, __float_as_int(v), 0x12F, 0xf, 0xf, false))
;     __device__ __forceinline__ void operator()(const f32x4 (&acc)[2][2][4][2], const Unit& u, int wr, int wc, int fr_in, int fq_in) const {
;     ...
;             for (int n = 0; n < 2; ++n) {
;                 const int ch = ch0 + 4 * n;
; #pragma unroll
;                 for (int pass = 0; pass < 2; ++pass) {
;                     const int co = pass ? DFF : 0;
;                     const f32x4 k0 = *(const f32x4*)(fk + co + ch), k1 = *(const f32x4*)(fk + DFF2 + co + ch), k2 = *(const f32x4*)(fk + 2 * DFF2 + co + ch), bb = *(const f32x4*)(fb + co + ch);
;                     f32x4 up_prev = (f32x4){0.f, 0.f, 0.f, 0.f}, up_cur, dn_cur, dn_next;
; #pragma unroll
;                     for (int j = 0; j < 4; ++j) dn_cur[j] = DPP_DN(acc[ai][pass][0][n][j]);
; #pragma unroll
;                     for (int m = 0; m < 4; ++m) {
;                         const f32x4 xv = acc[ai][pass][m][n];
; #pragma unroll
;                         for (int j = 0; j < 4; ++j) { up_cur[j] = DPP_UP(xv[j]); dn_next[j] = (m < 3) ? DPP_DN(acc[ai][pass][m < 3 ? m + 1 : 3][n][j]) : 0.f; }
;                         const f32x4 xp = f0 ? up_prev : up_cur, xn = f15 ? dn_next : dn_cur;
;                         const f32x4 c = (k0 * xp + k1 * xv) + (k2 * xn + bb);
;                         if (pass == 0) o[m] = c;
;                         else { f32x4 e;
; #pragma unroll
;                             for (int j = 0; j < 4; ++j) e[j] = __builtin_amdgcn_rcpf(1.0f + __builtin_amdgcn_exp2f(c[j] * -1.4426950408889634f));
;                             o[m] = o[m] * (c * e); }
;                         up_prev = up_cur; dn_cur = dn_next; }
.LBB0_1046:
	s_lshl_b32 s0, s42, 4
	s_mul_i32 s1, s42, 0x2c000
	s_mul_hi_i32 s0, s0, 0x2c00
	s_add_u32 s40, s46, s1
	s_addc_u32 s41, s64, s0
	v_mov_b32_e32 v96, v182
	v_mov_b32_e32 v130, v183
	s_lshl_b32 s0, s8, 7
	s_or_b32 s0, s0, s14
	v_lshl_add_u32 v158, v130, 3, s0
	v_add_u32_e32 v130, -14, v96
	v_cmp_gt_u32_e64 s[8:9], -12, v130
	v_cmp_gt_i32_e64 s[6:7], 2, v96
	v_add_u32_e32 v130, -12, v96
	v_ashrrev_i32_e32 v159, 31, v158
	v_cndmask_b32_e64 v130, v130, v96, s[6:7]
	v_add_u32_e32 v186, s17, v130
	v_mov_b64_e32 v[130:131], s[40:41]
	v_mad_i64_i32 v[166:167], s[0:1], v186, s45, v[130:131]
	v_lshlrev_b64 v[130:131], 2, v[158:159]
	v_lshl_add_u64 v[160:161], s[52:53], 0, v[130:131]
	v_lshl_add_u64 v[168:169], s[90:91], 0, v[130:131]
	v_lshl_add_u64 v[164:165], s[92:93], 0, v[130:131]
	v_lshl_add_u64 v[162:163], s[54:55], 0, v[130:131]
	global_load_dwordx4 v[134:137], v[160:161], off
	global_load_dwordx4 v[130:133], v[168:169], off
	global_load_dwordx4 v[138:141], v[164:165], off
	global_load_dwordx4 v[142:145], v[162:163], off
	v_cmp_eq_u32_e64 s[12:13], 15, v96
	v_mov_b32_dpp v170, v110 row_ror:15 row_mask:0xf bank_mask:0xf
	v_mov_b32_dpp v171, v111 row_ror:15 row_mask:0xf bank_mask:0xf
	v_mov_b32_dpp v179, v126 row_ror:15 row_mask:0xf bank_mask:0xf
	v_mov_b32_dpp v181, v127 row_ror:15 row_mask:0xf bank_mask:0xf
	v_cmp_eq_u32_e64 s[10:11], 0, v96
	v_mov_b32_dpp v178, v110 row_ror:1 row_mask:0xf bank_mask:0xf
	v_mov_b32_dpp v180, v111 row_ror:1 row_mask:0xf bank_mask:0xf
	v_mov_b32_dpp v187, v112 row_ror:1 row_mask:0xf bank_mask:0xf
	v_mov_b32_dpp v189, v113 row_ror:1 row_mask:0xf bank_mask:0xf
	v_cndmask_b32_e64 v171, v171, v181, s[12:13]
	v_cndmask_b32_e64 v170, v170, v179, s[12:13]
	v_mov_b32_dpp v172, v112 row_ror:15 row_mask:0xf bank_mask:0xf
	v_mov_b32_dpp v173, v113 row_ror:15 row_mask:0xf bank_mask:0xf
	v_mov_b32_dpp v188, v128 row_ror:15 row_mask:0xf bank_mask:0xf
	v_mov_b32_dpp v190, v129 row_ror:15 row_mask:0xf bank_mask:0xf
	v_cndmask_b32_e64 v177, v180, 0, s[10:11]
	v_cndmask_b32_e64 v176, v178, 0, s[10:11]
	v_cndmask_b32_e64 v173, v173, v190, s[12:13]
	v_cndmask_b32_e64 v172, v172, v188, s[12:13]
	v_mov_b32_dpp v192, v122 row_ror:15 row_mask:0xf bank_mask:0xf
	v_mov_b32_dpp v193, v127 row_ror:1 row_mask:0xf bank_mask:0xf
	v_mov_b32_dpp v194, v123 row_ror:15 row_mask:0xf bank_mask:0xf
	v_mov_b32_dpp v195, v128 row_ror:1 row_mask:0xf bank_mask:0xf
	v_mov_b32_dpp v198, v129 row_ror:1 row_mask:0xf bank_mask:0xf
	v_mov_b32_dpp v191, v126 row_ror:1 row_mask:0xf bank_mask:0xf
	v_mov_b32_dpp v197, v124 row_ror:15 row_mask:0xf bank_mask:0xf
	v_mov_b32_dpp v199, v125 row_ror:15 row_mask:0xf bank_mask:0xf
	v_cndmask_b32_e64 v178, v191, v178, s[10:11]
	v_mov_b32_dpp v200, v124 row_ror:1 row_mask:0xf bank_mask:0xf
	v_mov_b32_dpp v203, v125 row_ror:1 row_mask:0xf bank_mask:0xf
	v_mov_b32_dpp v202, v108 row_ror:15 row_mask:0xf bank_mask:0xf
	v_mov_b32_dpp v204, v109 row_ror:15 row_mask:0xf bank_mask:0xf
	v_mov_b32_dpp v205, v121 row_ror:15 row_mask:0xf bank_mask:0xf
	v_mov_b32_dpp v207, v119 row_ror:1 row_mask:0xf bank_mask:0xf
	v_mov_b32_dpp v209, v120 row_ror:1 row_mask:0xf bank_mask:0xf
	v_mov_b32_dpp v211, v121 row_ror:1 row_mask:0xf bank_mask:0xf
	v_mov_b32_dpp v206, v114 row_ror:15 row_mask:0xf bank_mask:0xf
	v_mov_b32_dpp v208, v115 row_ror:15 row_mask:0xf bank_mask:0xf
	v_mov_b32_dpp v210, v116 row_ror:15 row_mask:0xf bank_mask:0xf
	v_mov_b32_dpp v212, v117 row_ror:15 row_mask:0xf bank_mask:0xf
	s_waitcnt vmcnt(0)
	v_pk_mul_f32 v[176:177], v[134:135], v[176:177]
	s_nop 0
	v_pk_fma_f32 v[176:177], v[110:111], v[130:131], v[176:177]
	v_pk_fma_f32 v[174:175], v[138:139], v[170:171], v[142:143]
	v_cndmask_b32_e64 v171, v189, 0, s[10:11]
	v_cndmask_b32_e64 v170, v187, 0, s[10:11]
	v_pk_mul_f32 v[170:171], v[136:137], v[170:171]
	v_pk_fma_f32 v[172:173], v[140:141], v[172:173], v[144:145]
	v_pk_fma_f32 v[170:171], v[112:113], v[132:133], v[170:171]
	s_nop 0
	v_pk_add_f32 v[170:171], v[170:171], v[172:173]
	v_pk_add_f32 v[172:173], v[176:177], v[174:175]
	v_cndmask_b32_e64 v175, v181, v194, s[12:13]
	v_cndmask_b32_e64 v174, v179, v192, s[12:13]
	v_cndmask_b32_e64 v179, v193, v180, s[10:11]
	v_cndmask_b32_e64 v181, v198, v189, s[10:11]
	v_cndmask_b32_e64 v180, v195, v187, s[10:11]
	v_cndmask_b32_e64 v177, v190, v199, s[12:13]
	v_cndmask_b32_e64 v176, v188, v197, s[12:13]
	v_pk_mul_f32 v[180:181], v[136:137], v[180:181]
	v_pk_fma_f32 v[176:177], v[140:141], v[176:177], v[144:145]
	v_pk_mul_f32 v[178:179], v[134:135], v[178:179]
	v_pk_fma_f32 v[128:129], v[128:129], v[132:133], v[180:181]
	v_mov_b32_e32 v187, v97
	v_mov_b32_e32 v189, v97
	v_pk_fma_f32 v[174:175], v[138:139], v[174:175], v[142:143]
	v_pk_fma_f32 v[126:127], v[126:127], v[130:131], v[178:179]
	v_pk_add_f32 v[178:179], v[128:129], v[176:177]
	v_mov_b32_dpp v187, v122 row_ror:1 row_mask:0xf bank_mask:0xf
	v_mov_b32_dpp v189, v123 row_ror:1 row_mask:0xf bank_mask:0xf
	v_cndmask_b32_e64 v177, v203, v198, s[10:11]
	v_cndmask_b32_e64 v176, v200, v195, s[10:11]
	v_pk_add_f32 v[180:181], v[126:127], v[174:175]
	v_mov_b32_e32 v188, v97
	v_mov_b32_e32 v190, v97
	v_cndmask_b32_e64 v129, v199, v204, s[12:13]
	v_cndmask_b32_e64 v128, v197, v202, s[12:13]
	v_cndmask_b32_e64 v175, v189, v193, s[10:11]
	v_cndmask_b32_e64 v174, v187, v191, s[10:11]
	v_pk_mul_f32 v[176:177], v[136:137], v[176:177]
	v_mov_b32_dpp v188, v106 row_ror:15 row_mask:0xf bank_mask:0xf
	v_mov_b32_dpp v190, v107 row_ror:15 row_mask:0xf bank_mask:0xf
	v_pk_fma_f32 v[128:129], v[140:141], v[128:129], v[144:145]
	v_pk_mul_f32 v[174:175], v[134:135], v[174:175]
	v_pk_fma_f32 v[124:125], v[124:125], v[132:133], v[176:177]
; #define DPP_UP(v) __int_as_float(__builtin_amdgcn_update_dpp(0, __float_as_int(v), 0x121, 0xf, 0xf, false))
; #define DPP_DN(v) __int_as_float(__builtin_amdgcn_update_dpp(0, __float_as_int(v), 0x12F, 0xf, 0xf, false))
;     __device__ __forceinline__ void operator()(const f32x4 (&acc)[2][2][4][2], const Unit& u, int wr, int wc, int fr_in, int fq_in) const {
;     ...
;                 for (int pass = 0; pass < 2; ++pass) {
;                     const int co = pass ? DFF : 0;
;                     const f32x4 k0 = *(const f32x4*)(fk + co + ch), k1 = *(const f32x4*)(fk + DFF2 + co + ch), k2 = *(const f32x4*)(fk + 2 * DFF2 + co + ch), bb = *(const f32x4*)(fb + co + ch);
;                     f32x4 up_prev = (f32x4){0.f, 0.f, 0.f, 0.f}, up_cur, dn_cur, dn_next;
; #pragma unroll
;                     for (int j = 0; j < 4; ++j) dn_cur[j] = DPP_DN(acc[ai][pass][0][n][j]);
; #pragma unroll
;                     for (int m = 0; m < 4; ++m) {
;                         const f32x4 xv = acc[ai][pass][m][n];
; #pragma unroll
;                         for (int j = 0; j < 4; ++j) { up_cur[j] = DPP_UP(xv[j]); dn_next[j] = (m < 3) ? DPP_DN(acc[ai][pass][m < 3 ? m + 1 : 3][n][j]) : 0.f; }
;                         const f32x4 xp = f0 ? up_prev : up_cur, xn = f15 ? dn_next : dn_cur;
;                         const f32x4 c = (k0 * xp + k1 * xv) + (k2 * xn + bb);
;                         if (pass == 0) o[m] = c;
;                         else { f32x4 e;
; #pragma unroll
;                             for (int j = 0; j < 4; ++j) e[j] = __builtin_amdgcn_rcpf(1.0f + __builtin_amdgcn_exp2f(c[j] * -1.4426950408889634f));
;                             o[m] = o[m] * (c * e); }
;                         up_prev = up_cur; dn_cur = dn_next; }
	v_cndmask_b32_e64 v127, v194, v190, s[12:13]
	v_cndmask_b32_e64 v126, v192, v188, s[12:13]
	v_pk_fma_f32 v[122:123], v[122:123], v[130:131], v[174:175]
	v_pk_add_f32 v[174:175], v[124:125], v[128:129]
	v_mov_b32_e32 v128, v97
	v_mov_b32_e32 v129, v97
	v_pk_fma_f32 v[126:127], v[138:139], v[126:127], v[142:143]
	v_mov_b32_dpp v128, v108 row_ror:1 row_mask:0xf bank_mask:0xf
	v_mov_b32_dpp v129, v109 row_ror:1 row_mask:0xf bank_mask:0xf
	v_pk_add_f32 v[176:177], v[122:123], v[126:127]
	v_cndmask_b32_e64 v123, v204, 0, s[12:13]
	v_cndmask_b32_e64 v122, v202, 0, s[12:13]
	v_cndmask_b32_e64 v129, v129, v203, s[10:11]
	v_cndmask_b32_e64 v128, v128, v200, s[10:11]
	v_mov_b32_e32 v126, v97
	v_mov_b32_e32 v127, v97
	v_pk_fma_f32 v[122:123], v[140:141], v[122:123], v[144:145]
	v_pk_mul_f32 v[128:129], v[136:137], v[128:129]
	v_add_co_u32_e32 v140, vcc, s82, v160
	v_mov_b32_dpp v126, v106 row_ror:1 row_mask:0xf bank_mask:0xf
	v_mov_b32_dpp v127, v107 row_ror:1 row_mask:0xf bank_mask:0xf
	v_cndmask_b32_e64 v125, v190, 0, s[12:13]
	v_cndmask_b32_e64 v124, v188, 0, s[12:13]
	v_pk_fma_f32 v[128:129], v[108:109], v[132:133], v[128:129]
	v_addc_co_u32_e32 v141, vcc, 0, v161, vcc
	v_pk_fma_f32 v[124:125], v[138:139], v[124:125], v[142:143]
	v_cndmask_b32_e64 v127, v127, v189, s[10:11]
	v_cndmask_b32_e64 v126, v126, v187, s[10:11]
	v_pk_add_f32 v[142:143], v[122:123], v[128:129]
	v_add_co_u32_e32 v122, vcc, s82, v168
	v_pk_mul_f32 v[126:127], v[134:135], v[126:127]
	s_nop 0
	v_addc_co_u32_e32 v123, vcc, 0, v169, vcc
	v_pk_fma_f32 v[126:127], v[106:107], v[130:131], v[126:127]
	v_add_co_u32_e32 v130, vcc, s82, v164
	v_pk_add_f32 v[144:145], v[124:125], v[126:127]
	s_nop 0
	v_addc_co_u32_e32 v131, vcc, 0, v165, vcc
	v_add_co_u32_e32 v138, vcc, s82, v162
	global_load_dwordx4 v[126:129], v[140:141], off offset:3072
	s_nop 0
	v_addc_co_u32_e32 v139, vcc, 0, v163, vcc
	global_load_dwordx4 v[122:125], v[122:123], off offset:3072
	v_mov_b32_e32 v197, v97
	global_load_dwordx4 v[130:133], v[130:131], off offset:3072
	v_mov_b32_e32 v199, v97
	global_load_dwordx4 v[134:137], v[138:139], off offset:3072
	v_mov_b32_e32 v187, v97
	v_mov_b32_e32 v190, v97
	v_mov_b32_dpp v197, v102 row_ror:1 row_mask:0xf bank_mask:0xf
	v_mov_b32_e32 v198, v97
	v_mov_b32_dpp v199, v103 row_ror:1 row_mask:0xf bank_mask:0xf
	v_mov_b32_e32 v200, v97
	v_mov_b32_dpp v187, v102 row_ror:15 row_mask:0xf bank_mask:0xf
	v_mov_b32_dpp v190, v103 row_ror:15 row_mask:0xf bank_mask:0xf
	v_mov_b32_dpp v198, v118 row_ror:15 row_mask:0xf bank_mask:0xf
	v_mov_b32_dpp v200, v119 row_ror:15 row_mask:0xf bank_mask:0xf
	v_cndmask_b32_e64 v193, v199, 0, s[10:11]
	v_cndmask_b32_e64 v192, v197, 0, s[10:11]
	v_cndmask_b32_e64 v191, v190, v200, s[12:13]
	v_cndmask_b32_e64 v190, v187, v198, s[12:13]
	v_mov_b32_dpp v202, v104 row_ror:1 row_mask:0xf bank_mask:0xf
	v_mov_b32_e32 v203, v97
	v_mov_b32_dpp v204, v105 row_ror:1 row_mask:0xf bank_mask:0xf
	v_mov_b32_dpp v188, v104 row_ror:15 row_mask:0xf bank_mask:0xf
	v_mov_b32_dpp v189, v105 row_ror:15 row_mask:0xf bank_mask:0xf
	v_mov_b32_dpp v203, v120 row_ror:15 row_mask:0xf bank_mask:0xf
	v_cndmask_b32_e64 v195, v204, 0, s[10:11]
	v_cndmask_b32_e64 v194, v202, 0, s[10:11]
	v_cndmask_b32_e64 v189, v189, v205, s[12:13]
	v_cndmask_b32_e64 v188, v188, v203, s[12:13]
	s_waitcnt vmcnt(3)
	v_pk_mul_f32 v[192:193], v[126:127], v[192:193]
	v_pk_mul_f32 v[194:195], v[128:129], v[194:195]
	s_waitcnt vmcnt(2)
	v_pk_fma_f32 v[192:193], v[102:103], v[122:123], v[192:193]
	v_pk_fma_f32 v[194:195], v[104:105], v[124:125], v[194:195]
	s_waitcnt vmcnt(0)
	v_pk_fma_f32 v[190:191], v[130:131], v[190:191], v[134:135]
	s_nop 0
	v_pk_add_f32 v[190:191], v[192:193], v[190:191]
	v_pk_fma_f32 v[188:189], v[132:133], v[188:189], v[136:137]
	v_mul_f32_e32 v187, 0xbfb8aa3b, v190
	v_exp_f32_e32 v187, v187
	v_pk_add_f32 v[188:189], v[194:195], v[188:189]
	v_add_f32_e32 v187, 1.0, v187
	v_rcp_f32_e32 v192, v187
	v_mul_f32_e32 v187, 0xbfb8aa3b, v191
	v_exp_f32_e32 v187, v187
	s_nop 0
	v_add_f32_e32 v187, 1.0, v187
	v_rcp_f32_e32 v193, v187
	v_mul_f32_e32 v187, 0xbfb8aa3b, v188
	v_exp_f32_e32 v187, v187
	v_pk_mul_f32 v[190:191], v[190:191], v[192:193]
	v_cndmask_b32_e64 v193, v211, v204, s[10:11]
	v_add_f32_e32 v187, 1.0, v187
	v_rcp_f32_e32 v194, v187
	v_mul_f32_e32 v187, 0xbfb8aa3b, v189
	v_exp_f32_e32 v187, v187
	v_cndmask_b32_e64 v192, v209, v202, s[10:11]
	v_pk_mul_f32 v[172:173], v[172:173], v[190:191]
	v_cndmask_b32_e64 v191, v200, v208, s[12:13]
	v_add_f32_e32 v187, 1.0, v187
	v_rcp_f32_e32 v195, v187
	v_mov_b32_e32 v187, v97
	v_cndmask_b32_e64 v190, v198, v206, s[12:13]
	v_pk_mul_f32 v[192:193], v[128:129], v[192:193]
	v_mov_b32_dpp v187, v118 row_ror:1 row_mask:0xf bank_mask:0xf
	v_pk_mul_f32 v[188:189], v[188:189], v[194:195]
	v_cndmask_b32_e64 v195, v207, v199, s[10:11]
	v_cndmask_b32_e64 v194, v187, v197, s[10:11]
	v_pk_mul_f32 v[170:171], v[170:171], v[188:189]
	v_cndmask_b32_e64 v189, v205, v212, s[12:13]
	v_cndmask_b32_e64 v188, v203, v210, s[12:13]
	v_pk_mul_f32 v[194:195], v[126:127], v[194:195]
	v_pk_fma_f32 v[190:191], v[130:131], v[190:191], v[134:135]
	v_pk_fma_f32 v[188:189], v[132:133], v[188:189], v[136:137]
	v_pk_fma_f32 v[120:121], v[120:121], v[124:125], v[192:193]
	v_pk_fma_f32 v[118:119], v[118:119], v[122:123], v[194:195]
	v_pk_add_f32 v[120:121], v[120:121], v[188:189]
	v_pk_add_f32 v[118:119], v[118:119], v[190:191]
	v_mul_f32_e32 v190, 0xbfb8aa3b, v120
	v_mul_f32_e32 v188, 0xbfb8aa3b, v118
	v_mul_f32_e32 v189, 0xbfb8aa3b, v119
	v_mul_f32_e32 v191, 0xbfb8aa3b, v121
	v_exp_f32_e32 v188, v188
	v_exp_f32_e32 v189, v189
	v_exp_f32_e32 v190, v190
	v_exp_f32_e32 v191, v191
; __device__ __forceinline__ unsigned cvt_pk_bf16(float lo, float hi) { unsigned r; asm volatile("v_cvt_pk_bf16_f32 %0, %1, %2" : "=v"(r) : "v"(lo), "v"(hi)); return r; }
;     __device__ __forceinline__ void operator()(const f32x4 (&acc)[2][2][4][2], const Unit& u, int wr, int wc, int fr_in, int fq_in) const {
;     ...
;                         else { f32x4 e;
; #pragma unroll
;                             for (int j = 0; j < 4; ++j) e[j] = __builtin_amdgcn_rcpf(1.0f + __builtin_amdgcn_exp2f(c[j] * -1.4426950408889634f));
;                             o[m] = o[m] * (c * e); }
;                         up_prev = up_cur; dn_cur = dn_next; }
;                 }
;                 if (n == 0) {
; #pragma unroll
;                     for (int m = 0; m < 4; ++m) { wlo[m].x = cvt_pk_bf16(o[m][0], o[m][1]); wlo[m].y = cvt_pk_bf16(o[m][2], o[m][3]); }
;                 } else {
; #pragma unroll
;                     for (int m = 0; m < 4; ++m) { u32x4 w; w.x = wlo[m].x; w.y = wlo[m].y; w.z = cvt_pk_bf16(o[m][0], o[m][1]); w.w = cvt_pk_bf16(o[m][2], o[m][3]);
;                         *(u32x4*)(base + off0 + (unsigned)(ai * HALF + m * 16) * (DFF * 2u)) = w; }
;                 }
;                 if (fr < 2 || fr >= 14) { const int k = fr < 2 ? fr : fr - 12;
;                     const f32x4 xv = fr < 2 ? acc[ai][0][0][n] : acc[ai][0][3][n], yv = fr < 2 ? acc[ai][1][0][n] : acc[ai][1][3][n];
;                     char* sp = sbase + (size_t)((2 * ai + wr) * 4 + k) * (DFF2 * 2) + (size_t)ch * 2;
;                     u32x2 a, b; a.x = cvt_pk_bf16(xv[0], xv[1]); a.y = cvt_pk_bf16(xv[2], xv[3]); b.x = cvt_pk_bf16(yv[0], yv[1]); b.y = cvt_pk_bf16(yv[2], yv[3]);
;                     *(u32x2*)sp = a; *(u32x2*)(sp + DFF * 2) = b; }
	v_add_f32_e32 v188, 1.0, v188
	v_add_f32_e32 v189, 1.0, v189
	v_add_f32_e32 v190, 1.0, v190
	v_add_f32_e32 v191, 1.0, v191
	v_rcp_f32_e32 v188, v188
	v_rcp_f32_e32 v189, v189
	v_rcp_f32_e32 v190, v190
	v_rcp_f32_e32 v191, v191
	v_mov_b32_e32 v192, v97
	v_mov_b32_e32 v194, v97
	v_mov_b32_e32 v193, v97
	v_mov_b32_dpp v192, v114 row_ror:1 row_mask:0xf bank_mask:0xf
	v_mov_b32_dpp v194, v115 row_ror:1 row_mask:0xf bank_mask:0xf
	v_mov_b32_e32 v195, v97
	v_mov_b32_e32 v197, v97
	v_mov_b32_e32 v199, v97
	v_pk_mul_f32 v[120:121], v[120:121], v[190:191]
	v_pk_mul_f32 v[118:119], v[118:119], v[188:189]
	v_mov_b32_dpp v193, v98 row_ror:15 row_mask:0xf bank_mask:0xf
	v_mov_b32_dpp v195, v99 row_ror:15 row_mask:0xf bank_mask:0xf
	v_mov_b32_dpp v197, v116 row_ror:1 row_mask:0xf bank_mask:0xf
	v_mov_b32_e32 v198, v97
	v_mov_b32_dpp v199, v117 row_ror:1 row_mask:0xf bank_mask:0xf
	v_mov_b32_e32 v200, v97
	v_cndmask_b32_e64 v191, v194, v207, s[10:11]
	v_cndmask_b32_e64 v190, v192, v187, s[10:11]
	v_pk_mul_f32 v[118:119], v[180:181], v[118:119]
	v_mov_b32_dpp v198, v100 row_ror:15 row_mask:0xf bank_mask:0xf
	v_mov_b32_dpp v200, v101 row_ror:15 row_mask:0xf bank_mask:0xf
	v_cndmask_b32_e64 v181, v208, v195, s[12:13]
	v_cndmask_b32_e64 v180, v206, v193, s[12:13]
	v_cndmask_b32_e64 v189, v199, v211, s[10:11]
	v_cndmask_b32_e64 v188, v197, v209, s[10:11]
	v_pk_mul_f32 v[190:191], v[126:127], v[190:191]
	v_pk_mul_f32 v[178:179], v[178:179], v[120:121]
	v_cndmask_b32_e64 v121, v212, v200, s[12:13]
	v_cndmask_b32_e64 v120, v210, v198, s[12:13]
	v_pk_fma_f32 v[180:181], v[130:131], v[180:181], v[134:135]
	v_pk_mul_f32 v[188:189], v[128:129], v[188:189]
	v_pk_fma_f32 v[114:115], v[114:115], v[122:123], v[190:191]
	v_pk_fma_f32 v[120:121], v[132:133], v[120:121], v[136:137]
	v_pk_fma_f32 v[116:117], v[116:117], v[124:125], v[188:189]
	v_pk_add_f32 v[114:115], v[114:115], v[180:181]
	v_pk_add_f32 v[116:117], v[116:117], v[120:121]
	v_mul_f32_e32 v120, 0xbfb8aa3b, v114
	v_mul_f32_e32 v121, 0xbfb8aa3b, v115
	v_exp_f32_e32 v120, v120
	v_exp_f32_e32 v121, v121
	v_mul_f32_e32 v180, 0xbfb8aa3b, v116
	v_mul_f32_e32 v181, 0xbfb8aa3b, v117
	v_exp_f32_e32 v180, v180
	v_exp_f32_e32 v181, v181
	v_add_f32_e32 v120, 1.0, v120
	v_add_f32_e32 v121, 1.0, v121
	v_rcp_f32_e32 v120, v120
	v_rcp_f32_e32 v121, v121
	v_add_f32_e32 v180, 1.0, v180
	v_add_f32_e32 v181, 1.0, v181
	v_rcp_f32_e32 v180, v180
	v_rcp_f32_e32 v181, v181
	v_pk_mul_f32 v[114:115], v[114:115], v[120:121]
	v_cndmask_b32_e64 v121, v200, 0, s[12:13]
	v_pk_mul_f32 v[114:115], v[176:177], v[114:115]
	v_pk_mul_f32 v[116:117], v[116:117], v[180:181]
	v_mov_b32_e32 v176, v97
	v_mov_b32_e32 v177, v97
	v_mov_b32_e32 v180, v97
	v_mov_b32_e32 v181, v97
	v_pk_mul_f32 v[174:175], v[174:175], v[116:117]
	v_mov_b32_dpp v176, v98 row_ror:1 row_mask:0xf bank_mask:0xf
	v_mov_b32_dpp v177, v99 row_ror:1 row_mask:0xf bank_mask:0xf
	v_mov_b32_dpp v180, v100 row_ror:1 row_mask:0xf bank_mask:0xf
	v_mov_b32_dpp v181, v101 row_ror:1 row_mask:0xf bank_mask:0xf
	v_cndmask_b32_e64 v117, v195, 0, s[12:13]
	v_cndmask_b32_e64 v116, v193, 0, s[12:13]
	v_cndmask_b32_e64 v120, v198, 0, s[12:13]
	v_pk_fma_f32 v[120:121], v[132:133], v[120:121], v[136:137]
	v_pk_fma_f32 v[116:117], v[130:131], v[116:117], v[134:135]
	v_cndmask_b32_e64 v131, v181, v199, s[10:11]
	v_cndmask_b32_e64 v130, v180, v197, s[10:11]
	v_cndmask_b32_e64 v133, v177, v194, s[10:11]
	v_cndmask_b32_e64 v132, v176, v192, s[10:11]
	v_pk_mul_f32 v[126:127], v[126:127], v[132:133]
	v_pk_mul_f32 v[128:129], v[128:129], v[130:131]
	v_pk_fma_f32 v[122:123], v[98:99], v[122:123], v[126:127]
	v_pk_fma_f32 v[124:125], v[100:101], v[124:125], v[128:129]
	v_pk_add_f32 v[116:117], v[116:117], v[122:123]
	v_pk_add_f32 v[120:121], v[120:121], v[124:125]
	v_mul_f32_e32 v122, 0xbfb8aa3b, v116
	v_mul_f32_e32 v123, 0xbfb8aa3b, v117
	v_mul_f32_e32 v124, 0xbfb8aa3b, v120
	v_mul_f32_e32 v125, 0xbfb8aa3b, v121
	v_exp_f32_e32 v122, v122
	v_exp_f32_e32 v123, v123
	v_exp_f32_e32 v124, v124
	v_exp_f32_e32 v125, v125
	v_add_f32_e32 v122, 1.0, v122
	v_add_f32_e32 v123, 1.0, v123
	v_add_f32_e32 v124, 1.0, v124
	v_add_f32_e32 v125, 1.0, v125
	v_rcp_f32_e32 v122, v122
	v_rcp_f32_e32 v123, v123
	v_rcp_f32_e32 v124, v124
	v_rcp_f32_e32 v125, v125
	v_pk_mul_f32 v[116:117], v[116:117], v[122:123]
	v_pk_mul_f32 v[120:121], v[120:121], v[124:125]
	s_nop 0
	v_pk_mul_f32 v[122:123], v[142:143], v[120:121]
	v_pk_mul_f32 v[124:125], v[144:145], v[116:117]
	v_cvt_pk_bf16_f32 v120, v172, v173
	v_cvt_pk_bf16_f32 v121, v170, v171
	v_cvt_pk_bf16_f32 v118, v118, v119
	v_cvt_pk_bf16_f32 v119, v178, v179
	v_cvt_pk_bf16_f32 v116, v114, v115
	v_cvt_pk_bf16_f32 v117, v174, v175
	s_nop 0
	v_cvt_pk_bf16_f32 v114, v124, v125
	v_cvt_pk_bf16_f32 v115, v122, v123
	s_and_saveexec_b64 s[22:23], s[8:9]
	s_cbranch_execz .LBB0_1048
	v_cndmask_b32_e64 v102, v98, v102, s[6:7]
	v_cndmask_b32_e64 v103, v99, v103, s[6:7]
	v_lshl_add_u64 v[98:99], v[158:159], 1, v[166:167]
	v_cndmask_b32_e64 v108, v108, v112, s[6:7]
	v_cndmask_b32_e64 v109, v109, v113, s[6:7]
	v_cndmask_b32_e64 v106, v106, v110, s[6:7]
	v_cndmask_b32_e64 v107, v107, v111, s[6:7]
	v_cndmask_b32_e64 v104, v100, v104, s[6:7]
	v_cndmask_b32_e64 v105, v101, v105, s[6:7]
	v_cvt_pk_bf16_f32 v100, v106, v107
	v_cvt_pk_bf16_f32 v101, v108, v109
	v_cvt_pk_bf16_f32 v102, v102, v103
	v_cvt_pk_bf16_f32 v103, v104, v105
	global_store_dwordx2 v[98:99], v[100:101], off
	v_add_co_u32_e32 v98, vcc, 0x1000, v98
	s_nop 1
	v_addc_co_u32_e32 v99, vcc, 0, v99, vcc
	global_store_dwordx2 v[98:99], v[102:103], off offset:1536
; #define DPP_UP(v) __int_as_float(__builtin_amdgcn_update_dpp(0, __float_as_int(v), 0x121, 0xf, 0xf, false))
; #define DPP_DN(v) __int_as_float(__builtin_amdgcn_update_dpp(0, __float_as_int(v), 0x12F, 0xf, 0xf, false))
;     __device__ __forceinline__ void operator()(const f32x4 (&acc)[2][2][4][2], const Unit& u, int wr, int wc, int fr_in, int fq_in) const {
;     ...
;             for (int n = 0; n < 2; ++n) {
;                 const int ch = ch0 + 4 * n;
; #pragma unroll
;                 for (int pass = 0; pass < 2; ++pass) {
;                     const int co = pass ? DFF : 0;
;                     const f32x4 k0 = *(const f32x4*)(fk + co + ch), k1 = *(const f32x4*)(fk + DFF2 + co + ch), k2 = *(const f32x4*)(fk + 2 * DFF2 + co + ch), bb = *(const f32x4*)(fb + co + ch);
;                     f32x4 up_prev = (f32x4){0.f, 0.f, 0.f, 0.f}, up_cur, dn_cur, dn_next;
; #pragma unroll
;                     for (int j = 0; j < 4; ++j) dn_cur[j] = DPP_DN(acc[ai][pass][0][n][j]);
; #pragma unroll
;                     for (int m = 0; m < 4; ++m) {
;                         const f32x4 xv = acc[ai][pass][m][n];
; #pragma unroll
;                         for (int j = 0; j < 4; ++j) { up_cur[j] = DPP_UP(xv[j]); dn_next[j] = (m < 3) ? DPP_DN(acc[ai][pass][m < 3 ? m + 1 : 3][n][j]) : 0.f; }
;                         const f32x4 xp = f0 ? up_prev : up_cur, xn = f15 ? dn_next : dn_cur;
;                         const f32x4 c = (k0 * xp + k1 * xv) + (k2 * xn + bb);
;                         if (pass == 0) o[m] = c;
;                         else { f32x4 e;
; #pragma unroll
;                             for (int j = 0; j < 4; ++j) e[j] = __builtin_amdgcn_rcpf(1.0f + __builtin_amdgcn_exp2f(c[j] * -1.4426950408889634f));
;                             o[m] = o[m] * (c * e); }
;                         up_prev = up_cur; dn_cur = dn_next; }
.LBB0_1048:
	s_or_b64 exec, exec, s[22:23]
	v_or_b32_e32 v126, 4, v158
	v_ashrrev_i32_e32 v127, 31, v126
	v_lshlrev_b64 v[98:99], 2, v[126:127]
	v_lshl_add_u64 v[130:131], s[90:91], 0, v[98:99]
	v_lshl_add_u64 v[128:129], s[92:93], 0, v[98:99]
	global_load_dwordx4 v[102:105], v[160:161], off offset:16
	global_load_dwordx4 v[98:101], v[130:131], off
	global_load_dwordx4 v[106:109], v[128:129], off
	global_load_dwordx4 v[110:113], v[162:163], off offset:16
	v_mov_b32_dpp v170, v78 row_ror:1 row_mask:0xf bank_mask:0xf
	v_mov_b32_dpp v172, v79 row_ror:1 row_mask:0xf bank_mask:0xf
	v_mov_b32_dpp v132, v78 row_ror:15 row_mask:0xf bank_mask:0xf
	v_mov_b32_dpp v133, v79 row_ror:15 row_mask:0xf bank_mask:0xf
	v_mov_b32_dpp v144, v76 row_ror:1 row_mask:0xf bank_mask:0xf
	v_mov_b32_dpp v145, v77 row_ror:1 row_mask:0xf bank_mask:0xf
	v_mov_b32_dpp v171, v94 row_ror:15 row_mask:0xf bank_mask:0xf
	v_mov_b32_dpp v173, v95 row_ror:15 row_mask:0xf bank_mask:0xf
	v_cndmask_b32_e64 v135, v172, 0, s[10:11]
	v_cndmask_b32_e64 v134, v170, 0, s[10:11]
	v_mov_b32_dpp v122, v76 row_ror:15 row_mask:0xf bank_mask:0xf
	v_mov_b32_dpp v123, v77 row_ror:15 row_mask:0xf bank_mask:0xf
	v_mov_b32_dpp v142, v92 row_ror:15 row_mask:0xf bank_mask:0xf
	v_mov_b32_dpp v143, v93 row_ror:15 row_mask:0xf bank_mask:0xf
	v_cndmask_b32_e64 v133, v133, v173, s[12:13]
	v_cndmask_b32_e64 v132, v132, v171, s[12:13]
	v_cndmask_b32_e64 v137, v145, 0, s[10:11]
	v_cndmask_b32_e64 v136, v144, 0, s[10:11]
	v_mov_b32_e32 v175, v97
	v_mov_b32_e32 v177, v97
	v_mov_b32_e32 v178, v97
	v_mov_b32_e32 v180, v97
	v_cndmask_b32_e64 v123, v123, v143, s[12:13]
	v_cndmask_b32_e64 v122, v122, v142, s[12:13]
	v_mov_b32_e32 v174, v97
	v_mov_b32_dpp v175, v88 row_ror:15 row_mask:0xf bank_mask:0xf
	v_mov_b32_e32 v176, v97
	v_mov_b32_dpp v177, v89 row_ror:15 row_mask:0xf bank_mask:0xf
	v_mov_b32_dpp v178, v94 row_ror:1 row_mask:0xf bank_mask:0xf
	v_mov_b32_e32 v179, v97
	v_mov_b32_dpp v180, v95 row_ror:1 row_mask:0xf bank_mask:0xf
	v_mov_b32_e32 v181, v97
	v_mov_b32_dpp v174, v92 row_ror:1 row_mask:0xf bank_mask:0xf
	v_mov_b32_dpp v176, v93 row_ror:1 row_mask:0xf bank_mask:0xf
	v_mov_b32_dpp v179, v90 row_ror:15 row_mask:0xf bank_mask:0xf
	v_mov_b32_dpp v181, v91 row_ror:15 row_mask:0xf bank_mask:0xf
	v_cndmask_b32_e64 v145, v176, v145, s[10:11]
	v_cndmask_b32_e64 v144, v174, v144, s[10:11]
	v_mov_b32_dpp v187, v90 row_ror:1 row_mask:0xf bank_mask:0xf
	v_mov_b32_dpp v189, v91 row_ror:1 row_mask:0xf bank_mask:0xf
	v_mov_b32_dpp v188, v74 row_ror:15 row_mask:0xf bank_mask:0xf
	s_lshl_b32 s0, s42, 8
	v_mov_b32_dpp v190, v75 row_ror:15 row_mask:0xf bank_mask:0xf
	s_mul_i32 s1, s42, 0x160000
	v_readlane_b32 s22, v254, 37
	s_mul_hi_i32 s0, s0, 0x1600
	v_readlane_b32 s23, v254, 38
	s_add_u32 s42, s22, s1
	s_addc_u32 s43, s23, s0
	v_add_u32_e32 v96, s49, v96
	s_movk_i32 s0, 0x1600
	v_mul_lo_u32 v96, v96, s0
	v_lshl_add_u32 v96, v158, 1, v96
	v_lshl_add_u64 v[124:125], s[42:43], 0, v[96:97]
	s_mov_b32 s0, 0x16000
	s_waitcnt vmcnt(3)
	v_pk_mul_f32 v[134:135], v[104:105], v[134:135]
	v_pk_mul_f32 v[136:137], v[102:103], v[136:137]
	s_waitcnt vmcnt(2)
	v_pk_fma_f32 v[134:135], v[78:79], v[100:101], v[134:135]
	s_waitcnt vmcnt(0)
	v_pk_fma_f32 v[132:133], v[108:109], v[132:133], v[112:113]
	v_pk_fma_f32 v[122:123], v[106:107], v[122:123], v[110:111]
	v_pk_fma_f32 v[136:137], v[76:77], v[98:99], v[136:137]
	v_pk_add_f32 v[132:133], v[134:135], v[132:133]
	v_cndmask_b32_e64 v135, v143, v177, s[12:13]
	v_cndmask_b32_e64 v134, v142, v175, s[12:13]
	v_cndmask_b32_e64 v143, v180, v172, s[10:11]
	v_cndmask_b32_e64 v142, v178, v170, s[10:11]
	v_pk_add_f32 v[122:123], v[136:137], v[122:123]
	v_cndmask_b32_e64 v137, v173, v181, s[12:13]
	v_cndmask_b32_e64 v136, v171, v179, s[12:13]
	v_pk_mul_f32 v[142:143], v[104:105], v[142:143]
	v_mov_b32_e32 v170, v97
	v_mov_b32_e32 v172, v97
	v_pk_fma_f32 v[136:137], v[108:109], v[136:137], v[112:113]
	v_pk_mul_f32 v[144:145], v[102:103], v[144:145]
	v_pk_fma_f32 v[94:95], v[94:95], v[100:101], v[142:143]
	v_mov_b32_dpp v170, v88 row_ror:1 row_mask:0xf bank_mask:0xf
	v_mov_b32_e32 v171, v97
	v_mov_b32_dpp v172, v89 row_ror:1 row_mask:0xf bank_mask:0xf
	v_mov_b32_e32 v173, v97
	v_pk_fma_f32 v[134:135], v[106:107], v[134:135], v[110:111]
	v_pk_fma_f32 v[92:93], v[92:93], v[98:99], v[144:145]
	v_pk_add_f32 v[142:143], v[94:95], v[136:137]
	v_mov_b32_dpp v171, v72 row_ror:15 row_mask:0xf bank_mask:0xf
	v_mov_b32_dpp v173, v73 row_ror:15 row_mask:0xf bank_mask:0xf
	v_cndmask_b32_e64 v137, v172, v176, s[10:11]
	v_cndmask_b32_e64 v136, v170, v174, s[10:11]
	v_pk_add_f32 v[144:145], v[92:93], v[134:135]
	v_cndmask_b32_e64 v93, v177, v173, s[12:13]
	v_cndmask_b32_e64 v92, v175, v171, s[12:13]
	v_pk_mul_f32 v[136:137], v[102:103], v[136:137]
	v_pk_fma_f32 v[92:93], v[106:107], v[92:93], v[110:111]
	v_pk_fma_f32 v[88:89], v[88:89], v[98:99], v[136:137]
	v_cndmask_b32_e64 v135, v189, v180, s[10:11]
	v_cndmask_b32_e64 v134, v187, v178, s[10:11]
	v_pk_add_f32 v[136:137], v[88:89], v[92:93]
	v_mov_b32_e32 v92, v97
	v_mov_b32_e32 v93, v97
	v_cndmask_b32_e64 v95, v181, v190, s[12:13]
	v_cndmask_b32_e64 v94, v179, v188, s[12:13]
	v_pk_mul_f32 v[134:135], v[104:105], v[134:135]
	v_mov_b32_dpp v92, v74 row_ror:1 row_mask:0xf bank_mask:0xf
	v_mov_b32_dpp v93, v75 row_ror:1 row_mask:0xf bank_mask:0xf
	v_pk_fma_f32 v[94:95], v[108:109], v[94:95], v[112:113]
	v_pk_fma_f32 v[90:91], v[90:91], v[100:101], v[134:135]
	v_cndmask_b32_e64 v93, v93, v189, s[10:11]
	v_cndmask_b32_e64 v92, v92, v187, s[10:11]
	v_pk_add_f32 v[134:135], v[90:91], v[94:95]
	v_mov_b32_e32 v94, v97
	v_mov_b32_e32 v95, v97
	v_cndmask_b32_e64 v91, v190, 0, s[12:13]
; __device__ __forceinline__ unsigned cvt_pk_bf16(float lo, float hi) { unsigned r; asm volatile("v_cvt_pk_bf16_f32 %0, %1, %2" : "=v"(r) : "v"(lo), "v"(hi)); return r; }
; #define DPP_UP(v) __int_as_float(__builtin_amdgcn_update_dpp(0, __float_as_int(v), 0x121, 0xf, 0xf, false))
;     __device__ __forceinline__ void operator()(const f32x4 (&acc)[2][2][4][2], const Unit& u, int wr, int wc, int fr_in, int fq_in) const {
;     ...
;                 for (int pass = 0; pass < 2; ++pass) {
;                     const int co = pass ? DFF : 0;
;                     const f32x4 k0 = *(const f32x4*)(fk + co + ch), k1 = *(const f32x4*)(fk + DFF2 + co + ch), k2 = *(const f32x4*)(fk + 2 * DFF2 + co + ch), bb = *(const f32x4*)(fb + co + ch);
;                     f32x4 up_prev = (f32x4){0.f, 0.f, 0.f, 0.f}, up_cur, dn_cur, dn_next;
; #pragma unroll
;                     for (int j = 0; j < 4; ++j) dn_cur[j] = DPP_DN(acc[ai][pass][0][n][j]);
; #pragma unroll
;                     for (int m = 0; m < 4; ++m) {
;                         const f32x4 xv = acc[ai][pass][m][n];
; #pragma unroll
;                         for (int j = 0; j < 4; ++j) { up_cur[j] = DPP_UP(xv[j]); dn_next[j] = (m < 3) ? DPP_DN(acc[ai][pass][m < 3 ? m + 1 : 3][n][j]) : 0.f; }
;                         const f32x4 xp = f0 ? up_prev : up_cur, xn = f15 ? dn_next : dn_cur;
;                         const f32x4 c = (k0 * xp + k1 * xv) + (k2 * xn + bb);
;                         if (pass == 0) o[m] = c;
;                         else { f32x4 e;
; #pragma unroll
;                             for (int j = 0; j < 4; ++j) e[j] = __builtin_amdgcn_rcpf(1.0f + __builtin_amdgcn_exp2f(c[j] * -1.4426950408889634f));
;                             o[m] = o[m] * (c * e); }
;                         up_prev = up_cur; dn_cur = dn_next; }
;                 }
;                 if (n == 0) {
; #pragma unroll
;                     for (int m = 0; m < 4; ++m) { wlo[m].x = cvt_pk_bf16(o[m][0], o[m][1]); wlo[m].y = cvt_pk_bf16(o[m][2], o[m][3]); }
;                 } else {
; #pragma unroll
;                     for (int m = 0; m < 4; ++m) { u32x4 w; w.x = wlo[m].x; w.y = wlo[m].y; w.z = cvt_pk_bf16(o[m][0], o[m][1]); w.w = cvt_pk_bf16(o[m][2], o[m][3]);
;                         *(u32x4*)(base + off0 + (unsigned)(ai * HALF + m * 16) * (DFF * 2u)) = w; }
	v_cndmask_b32_e64 v90, v188, 0, s[12:13]
	v_pk_mul_f32 v[92:93], v[104:105], v[92:93]
	v_mov_b32_dpp v94, v72 row_ror:1 row_mask:0xf bank_mask:0xf
	v_mov_b32_dpp v95, v73 row_ror:1 row_mask:0xf bank_mask:0xf
	v_pk_fma_f32 v[90:91], v[108:109], v[90:91], v[112:113]
	v_pk_fma_f32 v[92:93], v[74:75], v[100:101], v[92:93]
	v_cndmask_b32_e64 v95, v95, v172, s[10:11]
	v_cndmask_b32_e64 v94, v94, v170, s[10:11]
	v_pk_add_f32 v[108:109], v[90:91], v[92:93]
	v_add_co_u32_e32 v92, vcc, s82, v130
	v_cndmask_b32_e64 v89, v173, 0, s[12:13]
	v_cndmask_b32_e64 v88, v171, 0, s[12:13]
	v_pk_mul_f32 v[94:95], v[102:103], v[94:95]
	v_addc_co_u32_e32 v93, vcc, 0, v131, vcc
	v_pk_fma_f32 v[88:89], v[106:107], v[88:89], v[110:111]
	v_pk_fma_f32 v[94:95], v[72:73], v[98:99], v[94:95]
	v_add_co_u32_e32 v98, vcc, s82, v128
	v_pk_add_f32 v[106:107], v[88:89], v[94:95]
	global_load_dwordx4 v[88:91], v[140:141], off offset:3088
	v_addc_co_u32_e32 v99, vcc, 0, v129, vcc
	global_load_dwordx4 v[92:95], v[92:93], off offset:3072
	s_nop 0
	global_load_dwordx4 v[98:101], v[98:99], off offset:3072
	s_nop 0
	global_load_dwordx4 v[102:105], v[138:139], off offset:3088
	v_mov_b32_dpp v170, v64 row_ror:1 row_mask:0xf bank_mask:0xf
	v_mov_b32_dpp v172, v65 row_ror:1 row_mask:0xf bank_mask:0xf
	v_mov_b32_dpp v174, v66 row_ror:1 row_mask:0xf bank_mask:0xf
	v_mov_b32_dpp v176, v67 row_ror:1 row_mask:0xf bank_mask:0xf
	v_mov_b32_dpp v112, v64 row_ror:15 row_mask:0xf bank_mask:0xf
	v_mov_b32_dpp v113, v65 row_ror:15 row_mask:0xf bank_mask:0xf
	v_mov_b32_dpp v110, v66 row_ror:15 row_mask:0xf bank_mask:0xf
	v_mov_b32_dpp v111, v67 row_ror:15 row_mask:0xf bank_mask:0xf
	v_mov_b32_dpp v171, v84 row_ror:15 row_mask:0xf bank_mask:0xf
	v_mov_b32_dpp v173, v85 row_ror:15 row_mask:0xf bank_mask:0xf
	v_mov_b32_dpp v175, v86 row_ror:15 row_mask:0xf bank_mask:0xf
	v_mov_b32_dpp v177, v87 row_ror:15 row_mask:0xf bank_mask:0xf
	v_cndmask_b32_e64 v139, v172, 0, s[10:11]
	v_cndmask_b32_e64 v138, v170, 0, s[10:11]
	v_cndmask_b32_e64 v141, v176, 0, s[10:11]
	v_cndmask_b32_e64 v140, v174, 0, s[10:11]
	v_cndmask_b32_e64 v111, v111, v177, s[12:13]
	v_cndmask_b32_e64 v110, v110, v175, s[12:13]
	v_cndmask_b32_e64 v113, v113, v173, s[12:13]
	v_cndmask_b32_e64 v112, v112, v171, s[12:13]
	v_mov_b32_dpp v178, v84 row_ror:1 row_mask:0xf bank_mask:0xf
	v_mov_b32_dpp v180, v85 row_ror:1 row_mask:0xf bank_mask:0xf
	v_mov_b32_dpp v187, v86 row_ror:1 row_mask:0xf bank_mask:0xf
	v_mov_b32_dpp v189, v87 row_ror:1 row_mask:0xf bank_mask:0xf
	v_mov_b32_dpp v179, v80 row_ror:15 row_mask:0xf bank_mask:0xf
	v_mov_b32_dpp v181, v81 row_ror:15 row_mask:0xf bank_mask:0xf
	v_mov_b32_dpp v188, v82 row_ror:15 row_mask:0xf bank_mask:0xf
	v_mov_b32_dpp v190, v83 row_ror:15 row_mask:0xf bank_mask:0xf
	s_waitcnt vmcnt(3)
	v_pk_mul_f32 v[140:141], v[90:91], v[140:141]
	v_pk_mul_f32 v[138:139], v[88:89], v[138:139]
	s_waitcnt vmcnt(2)
	v_pk_fma_f32 v[140:141], v[66:67], v[94:95], v[140:141]
	s_waitcnt vmcnt(0)
	v_pk_fma_f32 v[112:113], v[98:99], v[112:113], v[102:103]
	v_pk_fma_f32 v[110:111], v[100:101], v[110:111], v[104:105]
	v_pk_fma_f32 v[138:139], v[64:65], v[92:93], v[138:139]
	v_pk_add_f32 v[110:111], v[140:141], v[110:111]
	v_pk_add_f32 v[112:113], v[138:139], v[112:113]
	v_mul_f32_e32 v140, 0xbfb8aa3b, v110
	v_mul_f32_e32 v138, 0xbfb8aa3b, v112
	v_mul_f32_e32 v139, 0xbfb8aa3b, v113
	v_mul_f32_e32 v141, 0xbfb8aa3b, v111
	v_exp_f32_e32 v138, v138
	v_exp_f32_e32 v139, v139
	v_exp_f32_e32 v140, v140
	v_exp_f32_e32 v141, v141
	v_add_f32_e32 v138, 1.0, v138
	v_add_f32_e32 v139, 1.0, v139
	v_add_f32_e32 v140, 1.0, v140
	v_add_f32_e32 v141, 1.0, v141
	v_rcp_f32_e32 v138, v138
	v_rcp_f32_e32 v139, v139
	v_rcp_f32_e32 v140, v140
	v_rcp_f32_e32 v141, v141
	v_pk_mul_f32 v[112:113], v[112:113], v[138:139]
	v_cndmask_b32_e64 v139, v180, v172, s[10:11]
	v_pk_mul_f32 v[110:111], v[110:111], v[140:141]
	v_cndmask_b32_e64 v138, v178, v170, s[10:11]
	v_cndmask_b32_e64 v141, v189, v176, s[10:11]
	v_cndmask_b32_e64 v140, v187, v174, s[10:11]
	v_pk_mul_f32 v[110:111], v[132:133], v[110:111]
	v_pk_mul_f32 v[112:113], v[122:123], v[112:113]
	v_cndmask_b32_e64 v123, v177, v190, s[12:13]
	v_cndmask_b32_e64 v122, v175, v188, s[12:13]
	v_cndmask_b32_e64 v133, v173, v181, s[12:13]
	v_cndmask_b32_e64 v132, v171, v179, s[12:13]
	v_pk_mul_f32 v[140:141], v[90:91], v[140:141]
	v_pk_mul_f32 v[138:139], v[88:89], v[138:139]
	v_pk_fma_f32 v[132:133], v[98:99], v[132:133], v[102:103]
	v_pk_fma_f32 v[122:123], v[100:101], v[122:123], v[104:105]
	v_pk_fma_f32 v[86:87], v[86:87], v[94:95], v[140:141]
	v_pk_fma_f32 v[84:85], v[84:85], v[92:93], v[138:139]
	v_pk_add_f32 v[86:87], v[86:87], v[122:123]
	v_pk_add_f32 v[84:85], v[84:85], v[132:133]
	v_mul_f32_e32 v132, 0xbfb8aa3b, v86
	v_mul_f32_e32 v122, 0xbfb8aa3b, v84
	v_mul_f32_e32 v123, 0xbfb8aa3b, v85
	v_mul_f32_e32 v133, 0xbfb8aa3b, v87
	v_exp_f32_e32 v122, v122
	v_exp_f32_e32 v123, v123
	v_exp_f32_e32 v132, v132
	v_exp_f32_e32 v133, v133
	v_add_f32_e32 v122, 1.0, v122
	v_add_f32_e32 v123, 1.0, v123
	v_add_f32_e32 v132, 1.0, v132
	v_add_f32_e32 v133, 1.0, v133
	v_rcp_f32_e32 v122, v122
	v_rcp_f32_e32 v123, v123
	v_rcp_f32_e32 v132, v132
	v_rcp_f32_e32 v133, v133
	v_mov_b32_e32 v170, v97
	v_pk_mul_f32 v[122:123], v[84:85], v[122:123]
	v_mov_b32_e32 v172, v97
	v_pk_mul_f32 v[84:85], v[86:87], v[132:133]
	v_pk_mul_f32 v[86:87], v[144:145], v[122:123]
	v_pk_mul_f32 v[84:85], v[142:143], v[84:85]
	v_mov_b32_dpp v142, v80 row_ror:1 row_mask:0xf bank_mask:0xf
	v_mov_b32_dpp v144, v81 row_ror:1 row_mask:0xf bank_mask:0xf
	v_mov_b32_e32 v145, v97
	v_mov_b32_dpp v170, v82 row_ror:1 row_mask:0xf bank_mask:0xf
; __device__ __forceinline__ unsigned cvt_pk_bf16(float lo, float hi) { unsigned r; asm volatile("v_cvt_pk_bf16_f32 %0, %1, %2" : "=v"(r) : "v"(lo), "v"(hi)); return r; }
;     __device__ __forceinline__ void operator()(const f32x4 (&acc)[2][2][4][2], const Unit& u, int wr, int wc, int fr_in, int fq_in) const {
;     ...
;                         else { f32x4 e;
; #pragma unroll
;                             for (int j = 0; j < 4; ++j) e[j] = __builtin_amdgcn_rcpf(1.0f + __builtin_amdgcn_exp2f(c[j] * -1.4426950408889634f));
;                             o[m] = o[m] * (c * e); }
;                         up_prev = up_cur; dn_cur = dn_next; }
;                 }
;                 if (n == 0) {
; #pragma unroll
;                     for (int m = 0; m < 4; ++m) { wlo[m].x = cvt_pk_bf16(o[m][0], o[m][1]); wlo[m].y = cvt_pk_bf16(o[m][2], o[m][3]); }
;                 } else {
; #pragma unroll
;                     for (int m = 0; m < 4; ++m) { u32x4 w; w.x = wlo[m].x; w.y = wlo[m].y; w.z = cvt_pk_bf16(o[m][0], o[m][1]); w.w = cvt_pk_bf16(o[m][2], o[m][3]);
;                         *(u32x4*)(base + off0 + (unsigned)(ai * HALF + m * 16) * (DFF * 2u)) = w; }
;                 }
;                 if (fr < 2 || fr >= 14) { const int k = fr < 2 ? fr : fr - 12;
;                     const f32x4 xv = fr < 2 ? acc[ai][0][0][n] : acc[ai][0][3][n], yv = fr < 2 ? acc[ai][1][0][n] : acc[ai][1][3][n];
;                     char* sp = sbase + (size_t)((2 * ai + wr) * 4 + k) * (DFF2 * 2) + (size_t)ch * 2;
;                     u32x2 a, b; a.x = cvt_pk_bf16(xv[0], xv[1]); a.y = cvt_pk_bf16(xv[2], xv[3]); b.x = cvt_pk_bf16(yv[0], yv[1]); b.y = cvt_pk_bf16(yv[2], yv[3]);
;                     *(u32x2*)sp = a; *(u32x2*)(sp + DFF * 2) = b; }
	v_mov_b32_e32 v171, v97
	v_mov_b32_dpp v172, v83 row_ror:1 row_mask:0xf bank_mask:0xf
	v_mov_b32_e32 v173, v97
	v_mov_b32_dpp v143, v68 row_ror:15 row_mask:0xf bank_mask:0xf
	v_mov_b32_dpp v145, v69 row_ror:15 row_mask:0xf bank_mask:0xf
	v_mov_b32_dpp v171, v70 row_ror:15 row_mask:0xf bank_mask:0xf
	v_mov_b32_dpp v173, v71 row_ror:15 row_mask:0xf bank_mask:0xf
	v_cndmask_b32_e64 v139, v144, v180, s[10:11]
	v_cndmask_b32_e64 v138, v142, v178, s[10:11]
	v_cndmask_b32_e64 v141, v172, v189, s[10:11]
	v_cndmask_b32_e64 v140, v170, v187, s[10:11]
	v_cndmask_b32_e64 v123, v190, v173, s[12:13]
	v_cndmask_b32_e64 v122, v188, v171, s[12:13]
	v_cndmask_b32_e64 v133, v181, v145, s[12:13]
	v_cndmask_b32_e64 v132, v179, v143, s[12:13]
	v_pk_mul_f32 v[140:141], v[90:91], v[140:141]
	v_pk_mul_f32 v[138:139], v[88:89], v[138:139]
	v_pk_fma_f32 v[132:133], v[98:99], v[132:133], v[102:103]
	v_pk_fma_f32 v[122:123], v[100:101], v[122:123], v[104:105]
	v_pk_fma_f32 v[82:83], v[82:83], v[94:95], v[140:141]
	v_pk_fma_f32 v[80:81], v[80:81], v[92:93], v[138:139]
	v_pk_add_f32 v[82:83], v[82:83], v[122:123]
	v_pk_add_f32 v[80:81], v[80:81], v[132:133]
	v_mul_f32_e32 v132, 0xbfb8aa3b, v82
	v_mul_f32_e32 v122, 0xbfb8aa3b, v80
	v_mul_f32_e32 v123, 0xbfb8aa3b, v81
	v_mul_f32_e32 v133, 0xbfb8aa3b, v83
	v_exp_f32_e32 v122, v122
	v_exp_f32_e32 v123, v123
	v_exp_f32_e32 v132, v132
	v_exp_f32_e32 v133, v133
	v_add_f32_e32 v122, 1.0, v122
	v_add_f32_e32 v123, 1.0, v123
	v_add_f32_e32 v132, 1.0, v132
	v_add_f32_e32 v133, 1.0, v133
	v_rcp_f32_e32 v122, v122
	v_rcp_f32_e32 v123, v123
	v_rcp_f32_e32 v132, v132
	v_rcp_f32_e32 v133, v133
	v_pk_mul_f32 v[80:81], v[80:81], v[122:123]
	s_nop 0
	v_pk_mul_f32 v[80:81], v[136:137], v[80:81]
	v_pk_mul_f32 v[82:83], v[82:83], v[132:133]
	v_mov_b32_e32 v136, v97
	v_pk_mul_f32 v[82:83], v[134:135], v[82:83]
	v_mov_b32_e32 v134, v97
	v_mov_b32_e32 v135, v97
	v_mov_b32_e32 v137, v97
	v_mov_b32_dpp v134, v68 row_ror:1 row_mask:0xf bank_mask:0xf
	v_mov_b32_dpp v135, v69 row_ror:1 row_mask:0xf bank_mask:0xf
	v_mov_b32_dpp v136, v70 row_ror:1 row_mask:0xf bank_mask:0xf
	v_mov_b32_dpp v137, v71 row_ror:1 row_mask:0xf bank_mask:0xf
	v_cndmask_b32_e64 v123, v145, 0, s[12:13]
	v_cndmask_b32_e64 v122, v143, 0, s[12:13]
	v_cndmask_b32_e64 v133, v173, 0, s[12:13]
	v_cndmask_b32_e64 v132, v171, 0, s[12:13]
	v_pk_fma_f32 v[100:101], v[100:101], v[132:133], v[104:105]
	v_pk_fma_f32 v[98:99], v[98:99], v[122:123], v[102:103]
	v_cndmask_b32_e64 v103, v135, v144, s[10:11]
	v_cndmask_b32_e64 v102, v134, v142, s[10:11]
	v_cndmask_b32_e64 v105, v137, v172, s[10:11]
	v_cndmask_b32_e64 v104, v136, v170, s[10:11]
	v_pk_mul_f32 v[90:91], v[90:91], v[104:105]
	v_pk_mul_f32 v[88:89], v[88:89], v[102:103]
	v_pk_fma_f32 v[90:91], v[70:71], v[94:95], v[90:91]
	v_pk_fma_f32 v[88:89], v[68:69], v[92:93], v[88:89]
	v_pk_add_f32 v[90:91], v[100:101], v[90:91]
	v_pk_add_f32 v[88:89], v[98:99], v[88:89]
	v_mul_f32_e32 v94, 0xbfb8aa3b, v90
	v_mul_f32_e32 v92, 0xbfb8aa3b, v88
	v_mul_f32_e32 v93, 0xbfb8aa3b, v89
	v_mul_f32_e32 v95, 0xbfb8aa3b, v91
	v_exp_f32_e32 v92, v92
	v_exp_f32_e32 v93, v93
	v_exp_f32_e32 v94, v94
	v_exp_f32_e32 v95, v95
	v_add_f32_e32 v92, 1.0, v92
	v_add_f32_e32 v93, 1.0, v93
	v_add_f32_e32 v94, 1.0, v94
	v_add_f32_e32 v95, 1.0, v95
	v_cvt_pk_bf16_f32 v122, v112, v113
	v_cvt_pk_bf16_f32 v123, v110, v111
	global_store_dwordx4 v96, v[120:123], s[42:43]
	v_rcp_f32_e32 v92, v92
	v_rcp_f32_e32 v93, v93
	v_cvt_pk_bf16_f32 v120, v86, v87
	v_cvt_pk_bf16_f32 v121, v84, v85
	v_add_co_u32_e32 v84, vcc, s0, v124
	v_rcp_f32_e32 v94, v94
	v_rcp_f32_e32 v95, v95
	v_addc_co_u32_e32 v85, vcc, 0, v125, vcc
	s_mov_b32 s0, 0x2c000
	global_store_dwordx4 v[84:85], v[118:121], off
	v_pk_mul_f32 v[90:91], v[90:91], v[94:95]
	v_pk_mul_f32 v[88:89], v[88:89], v[92:93]
	v_cvt_pk_bf16_f32 v118, v80, v81
	v_add_co_u32_e32 v80, vcc, s0, v124
	v_cvt_pk_bf16_f32 v119, v82, v83
	v_pk_mul_f32 v[90:91], v[108:109], v[90:91]
	s_nop 0
	v_addc_co_u32_e32 v81, vcc, 0, v125, vcc
	global_store_dwordx4 v[80:81], v[116:119], off
	v_add_co_u32_e32 v80, vcc, 0x42000, v124
	v_pk_mul_f32 v[88:89], v[106:107], v[88:89]
	s_nop 0
	v_addc_co_u32_e32 v81, vcc, 0, v125, vcc
	v_cvt_pk_bf16_f32 v116, v88, v89
	v_cvt_pk_bf16_f32 v117, v90, v91
	global_store_dwordx4 v[80:81], v[114:117], off
	s_and_saveexec_b64 s[22:23], s[8:9]
	s_cbranch_execz .LBB0_1050
	v_cndmask_b32_e64 v68, v68, v64, s[6:7]
	v_cndmask_b32_e64 v69, v69, v65, s[6:7]
	v_lshl_add_u64 v[64:65], v[126:127], 1, v[166:167]
	v_cndmask_b32_e64 v74, v74, v78, s[6:7]
	v_cndmask_b32_e64 v75, v75, v79, s[6:7]
	v_cndmask_b32_e64 v72, v72, v76, s[6:7]
	v_cndmask_b32_e64 v73, v73, v77, s[6:7]
	v_cndmask_b32_e64 v70, v70, v66, s[6:7]
	v_cndmask_b32_e64 v71, v71, v67, s[6:7]
	v_cvt_pk_bf16_f32 v66, v72, v73
	v_cvt_pk_bf16_f32 v67, v74, v75
	v_cvt_pk_bf16_f32 v68, v68, v69
	v_cvt_pk_bf16_f32 v69, v70, v71
	global_store_dwordx2 v[64:65], v[66:67], off
	v_add_co_u32_e32 v64, vcc, 0x1000, v64
	s_nop 1
	v_addc_co_u32_e32 v65, vcc, 0, v65, vcc
	global_store_dwordx2 v[64:65], v[68:69], off offset:1536
; #define DPP_UP(v) __int_as_float(__builtin_amdgcn_update_dpp(0, __float_as_int(v), 0x121, 0xf, 0xf, false))
; #define DPP_DN(v) __int_as_float(__builtin_amdgcn_update_dpp(0, __float_as_int(v), 0x12F, 0xf, 0xf, false))
;     __device__ __forceinline__ void operator()(const f32x4 (&acc)[2][2][4][2], const Unit& u, int wr, int wc, int fr_in, int fq_in) const {
;     ...
;         for (int ai = 0; ai < 2; ++ai) {
;             f32x4 o[4]; u32x2 wlo[4];
; #pragma unroll
;             for (int n = 0; n < 2; ++n) {
;                 const int ch = ch0 + 4 * n;
; #pragma unroll
;                 for (int pass = 0; pass < 2; ++pass) {
;                     const int co = pass ? DFF : 0;
;                     const f32x4 k0 = *(const f32x4*)(fk + co + ch), k1 = *(const f32x4*)(fk + DFF2 + co + ch), k2 = *(const f32x4*)(fk + 2 * DFF2 + co + ch), bb = *(const f32x4*)(fb + co + ch);
;                     f32x4 up_prev = (f32x4){0.f, 0.f, 0.f, 0.f}, up_cur, dn_cur, dn_next;
; #pragma unroll
;                     for (int j = 0; j < 4; ++j) dn_cur[j] = DPP_DN(acc[ai][pass][0][n][j]);
; #pragma unroll
;                     for (int m = 0; m < 4; ++m) {
;                         const f32x4 xv = acc[ai][pass][m][n];
; #pragma unroll
;                         for (int j = 0; j < 4; ++j) { up_cur[j] = DPP_UP(xv[j]); dn_next[j] = (m < 3) ? DPP_DN(acc[ai][pass][m < 3 ? m + 1 : 3][n][j]) : 0.f; }
;                         const f32x4 xp = f0 ? up_prev : up_cur, xn = f15 ? dn_next : dn_cur;
;                         const f32x4 c = (k0 * xp + k1 * xv) + (k2 * xn + bb);
;                         if (pass == 0) o[m] = c;
;                         else { f32x4 e;
; #pragma unroll
;                             for (int j = 0; j < 4; ++j) e[j] = __builtin_amdgcn_rcpf(1.0f + __builtin_amdgcn_exp2f(c[j] * -1.4426950408889634f));
;                             o[m] = o[m] * (c * e); }
;                         up_prev = up_cur; dn_cur = dn_next; }
.LBB0_1050:
	s_or_b64 exec, exec, s[22:23]
	s_mov_b64 s[0:1], 0x2c00
	v_add_u32_e32 v66, 8, v186
	v_mov_b64_e32 v[64:65], s[40:41]
	v_lshl_add_u64 v[100:101], v[160:161], 0, s[0:1]
	v_lshl_add_u64 v[102:103], v[168:169], 0, s[0:1]
	v_lshl_add_u64 v[90:91], v[164:165], 0, s[0:1]
	v_lshl_add_u64 v[92:93], v[162:163], 0, s[0:1]
	v_mad_i64_i32 v[80:81], s[0:1], v66, s45, v[64:65]
	global_load_dwordx4 v[68:71], v[160:161], off
	global_load_dwordx4 v[64:67], v[168:169], off
	global_load_dwordx4 v[72:75], v[164:165], off
	global_load_dwordx4 v[76:79], v[162:163], off
	v_mov_b32_dpp v99, v46 row_ror:1 row_mask:0xf bank_mask:0xf
	v_mov_b32_dpp v105, v47 row_ror:1 row_mask:0xf bank_mask:0xf
	v_mov_b32_dpp v84, v46 row_ror:15 row_mask:0xf bank_mask:0xf
	v_mov_b32_dpp v85, v47 row_ror:15 row_mask:0xf bank_mask:0xf
	v_mov_b32_dpp v96, v44 row_ror:1 row_mask:0xf bank_mask:0xf
	v_mov_b32_dpp v98, v45 row_ror:1 row_mask:0xf bank_mask:0xf
	v_mov_b32_dpp v104, v62 row_ror:15 row_mask:0xf bank_mask:0xf
	v_mov_b32_dpp v106, v63 row_ror:15 row_mask:0xf bank_mask:0xf
	v_cndmask_b32_e64 v87, v105, 0, s[10:11]
	v_cndmask_b32_e64 v86, v99, 0, s[10:11]
	v_mov_b32_dpp v82, v44 row_ror:15 row_mask:0xf bank_mask:0xf
	v_mov_b32_dpp v83, v45 row_ror:15 row_mask:0xf bank_mask:0xf
	v_mov_b32_dpp v94, v60 row_ror:15 row_mask:0xf bank_mask:0xf
	v_mov_b32_dpp v95, v61 row_ror:15 row_mask:0xf bank_mask:0xf
	v_cndmask_b32_e64 v85, v85, v106, s[12:13]
	v_cndmask_b32_e64 v84, v84, v104, s[12:13]
	v_cndmask_b32_e64 v89, v98, 0, s[10:11]
	v_cndmask_b32_e64 v88, v96, 0, s[10:11]
	v_cndmask_b32_e64 v83, v83, v95, s[12:13]
	v_cndmask_b32_e64 v82, v82, v94, s[12:13]
	v_mov_b32_dpp v107, v60 row_ror:1 row_mask:0xf bank_mask:0xf
	v_mov_b32_dpp v108, v56 row_ror:15 row_mask:0xf bank_mask:0xf
	v_mov_b32_dpp v109, v61 row_ror:1 row_mask:0xf bank_mask:0xf
	v_mov_b32_dpp v110, v57 row_ror:15 row_mask:0xf bank_mask:0xf
	v_mov_b32_dpp v111, v62 row_ror:1 row_mask:0xf bank_mask:0xf
	v_mov_b32_dpp v113, v63 row_ror:1 row_mask:0xf bank_mask:0xf
	v_mov_b32_dpp v112, v58 row_ror:15 row_mask:0xf bank_mask:0xf
	v_mov_b32_dpp v114, v59 row_ror:15 row_mask:0xf bank_mask:0xf
	v_mov_b32_dpp v115, v58 row_ror:1 row_mask:0xf bank_mask:0xf
	v_mov_b32_dpp v117, v59 row_ror:1 row_mask:0xf bank_mask:0xf
	v_mov_b32_dpp v116, v42 row_ror:15 row_mask:0xf bank_mask:0xf
	s_waitcnt vmcnt(3)
	v_pk_mul_f32 v[86:87], v[70:71], v[86:87]
	v_pk_mul_f32 v[88:89], v[68:69], v[88:89]
	s_waitcnt vmcnt(2)
	v_pk_fma_f32 v[86:87], v[46:47], v[66:67], v[86:87]
	s_waitcnt vmcnt(0)
	v_pk_fma_f32 v[84:85], v[74:75], v[84:85], v[78:79]
	v_pk_fma_f32 v[82:83], v[72:73], v[82:83], v[76:77]
	v_pk_fma_f32 v[88:89], v[44:45], v[64:65], v[88:89]
	v_pk_add_f32 v[84:85], v[86:87], v[84:85]
	v_cndmask_b32_e64 v87, v95, v110, s[12:13]
	v_cndmask_b32_e64 v86, v94, v108, s[12:13]
	v_cndmask_b32_e64 v95, v113, v105, s[10:11]
	v_cndmask_b32_e64 v94, v111, v99, s[10:11]
	v_cndmask_b32_e64 v99, v109, v98, s[10:11]
	v_cndmask_b32_e64 v98, v107, v96, s[10:11]
	v_pk_add_f32 v[82:83], v[88:89], v[82:83]
	v_cndmask_b32_e64 v89, v106, v114, s[12:13]
	v_cndmask_b32_e64 v88, v104, v112, s[12:13]
	v_pk_mul_f32 v[98:99], v[68:69], v[98:99]
	v_pk_mul_f32 v[94:95], v[70:71], v[94:95]
	v_mov_b32_e32 v96, v97
	v_mov_b32_e32 v105, v97
	v_pk_fma_f32 v[88:89], v[74:75], v[88:89], v[78:79]
	v_pk_fma_f32 v[86:87], v[72:73], v[86:87], v[76:77]
	v_pk_fma_f32 v[62:63], v[62:63], v[66:67], v[94:95]
	v_pk_fma_f32 v[60:61], v[60:61], v[64:65], v[98:99]
	v_mov_b32_dpp v96, v56 row_ror:1 row_mask:0xf bank_mask:0xf
	v_mov_b32_e32 v104, v97
	v_mov_b32_dpp v105, v57 row_ror:1 row_mask:0xf bank_mask:0xf
	v_mov_b32_e32 v106, v97
	v_pk_add_f32 v[94:95], v[60:61], v[86:87]
	v_pk_add_f32 v[98:99], v[62:63], v[88:89]
	v_mov_b32_dpp v104, v40 row_ror:15 row_mask:0xf bank_mask:0xf
	v_mov_b32_dpp v106, v41 row_ror:15 row_mask:0xf bank_mask:0xf
	v_mov_b32_dpp v118, v43 row_ror:15 row_mask:0xf bank_mask:0xf
	v_cndmask_b32_e64 v87, v117, v113, s[10:11]
	v_cndmask_b32_e64 v86, v115, v111, s[10:11]
	v_cndmask_b32_e64 v89, v105, v109, s[10:11]
	v_cndmask_b32_e64 v88, v96, v107, s[10:11]
	v_cndmask_b32_e64 v61, v110, v106, s[12:13]
	v_cndmask_b32_e64 v60, v108, v104, s[12:13]
	v_cndmask_b32_e64 v63, v114, v118, s[12:13]
	v_cndmask_b32_e64 v62, v112, v116, s[12:13]
	v_pk_mul_f32 v[88:89], v[68:69], v[88:89]
	v_pk_mul_f32 v[86:87], v[70:71], v[86:87]
	v_pk_fma_f32 v[62:63], v[74:75], v[62:63], v[78:79]
	v_pk_fma_f32 v[60:61], v[72:73], v[60:61], v[76:77]
	v_pk_fma_f32 v[58:59], v[58:59], v[66:67], v[86:87]
	v_pk_fma_f32 v[56:57], v[56:57], v[64:65], v[88:89]
	v_pk_add_f32 v[88:89], v[58:59], v[62:63]
	v_pk_add_f32 v[86:87], v[56:57], v[60:61]
	v_mov_b32_e32 v62, v97
	v_mov_b32_e32 v63, v97
	v_mov_b32_e32 v60, v97
	v_mov_b32_e32 v61, v97
	v_mov_b32_dpp v62, v40 row_ror:1 row_mask:0xf bank_mask:0xf
	v_mov_b32_dpp v63, v41 row_ror:1 row_mask:0xf bank_mask:0xf
	v_mov_b32_dpp v60, v42 row_ror:1 row_mask:0xf bank_mask:0xf
	v_mov_b32_dpp v61, v43 row_ror:1 row_mask:0xf bank_mask:0xf
	v_cndmask_b32_e64 v61, v61, v117, s[10:11]
	v_cndmask_b32_e64 v60, v60, v115, s[10:11]
	v_cndmask_b32_e64 v63, v63, v105, s[10:11]
	v_cndmask_b32_e64 v62, v62, v96, s[10:11]
	v_cndmask_b32_e64 v57, v106, 0, s[12:13]
	v_cndmask_b32_e64 v56, v104, 0, s[12:13]
	v_cndmask_b32_e64 v59, v118, 0, s[12:13]
	v_cndmask_b32_e64 v58, v116, 0, s[12:13]
	v_pk_mul_f32 v[62:63], v[68:69], v[62:63]
	v_pk_mul_f32 v[60:61], v[70:71], v[60:61]
	v_pk_fma_f32 v[58:59], v[74:75], v[58:59], v[78:79]
	v_pk_fma_f32 v[56:57], v[72:73], v[56:57], v[76:77]
	v_pk_fma_f32 v[60:61], v[42:43], v[66:67], v[60:61]
	v_pk_fma_f32 v[62:63], v[40:41], v[64:65], v[62:63]
; #define DPP_UP(v) __int_as_float(__builtin_amdgcn_update_dpp(0, __float_as_int(v), 0x121, 0xf, 0xf, false))
; #define DPP_DN(v) __int_as_float(__builtin_amdgcn_update_dpp(0, __float_as_int(v), 0x12F, 0xf, 0xf, false))
;     __device__ __forceinline__ void operator()(const f32x4 (&acc)[2][2][4][2], const Unit& u, int wr, int wc, int fr_in, int fq_in) const {
;     ...
;                 for (int pass = 0; pass < 2; ++pass) {
;                     const int co = pass ? DFF : 0;
;                     const f32x4 k0 = *(const f32x4*)(fk + co + ch), k1 = *(const f32x4*)(fk + DFF2 + co + ch), k2 = *(const f32x4*)(fk + 2 * DFF2 + co + ch), bb = *(const f32x4*)(fb + co + ch);
;                     f32x4 up_prev = (f32x4){0.f, 0.f, 0.f, 0.f}, up_cur, dn_cur, dn_next;
; #pragma unroll
;                     for (int j = 0; j < 4; ++j) dn_cur[j] = DPP_DN(acc[ai][pass][0][n][j]);
; #pragma unroll
;                     for (int m = 0; m < 4; ++m) {
;                         const f32x4 xv = acc[ai][pass][m][n];
; #pragma unroll
;                         for (int j = 0; j < 4; ++j) { up_cur[j] = DPP_UP(xv[j]); dn_next[j] = (m < 3) ? DPP_DN(acc[ai][pass][m < 3 ? m + 1 : 3][n][j]) : 0.f; }
;                         const f32x4 xp = f0 ? up_prev : up_cur, xn = f15 ? dn_next : dn_cur;
;                         const f32x4 c = (k0 * xp + k1 * xv) + (k2 * xn + bb);
;                         if (pass == 0) o[m] = c;
;                         else { f32x4 e;
; #pragma unroll
;                             for (int j = 0; j < 4; ++j) e[j] = __builtin_amdgcn_rcpf(1.0f + __builtin_amdgcn_exp2f(c[j] * -1.4426950408889634f));
;                             o[m] = o[m] * (c * e); }
;                         up_prev = up_cur; dn_cur = dn_next; }
	v_pk_add_f32 v[74:75], v[58:59], v[60:61]
	v_pk_add_f32 v[72:73], v[56:57], v[62:63]
	global_load_dwordx4 v[60:63], v[100:101], off
	global_load_dwordx4 v[56:59], v[102:103], off
	global_load_dwordx4 v[64:67], v[90:91], off
	global_load_dwordx4 v[68:71], v[92:93], off
	v_mov_b32_dpp v96, v36 row_ror:1 row_mask:0xf bank_mask:0xf
	v_mov_b32_dpp v101, v37 row_ror:1 row_mask:0xf bank_mask:0xf
	v_mov_b32_dpp v103, v38 row_ror:1 row_mask:0xf bank_mask:0xf
	v_mov_b32_dpp v105, v39 row_ror:1 row_mask:0xf bank_mask:0xf
	v_mov_b32_dpp v78, v36 row_ror:15 row_mask:0xf bank_mask:0xf
	v_mov_b32_dpp v79, v37 row_ror:15 row_mask:0xf bank_mask:0xf
	v_mov_b32_dpp v76, v38 row_ror:15 row_mask:0xf bank_mask:0xf
	v_mov_b32_dpp v77, v39 row_ror:15 row_mask:0xf bank_mask:0xf
	v_mov_b32_dpp v100, v52 row_ror:15 row_mask:0xf bank_mask:0xf
	v_mov_b32_dpp v102, v53 row_ror:15 row_mask:0xf bank_mask:0xf
	v_mov_b32_dpp v104, v54 row_ror:15 row_mask:0xf bank_mask:0xf
	v_mov_b32_dpp v106, v55 row_ror:15 row_mask:0xf bank_mask:0xf
	v_cndmask_b32_e64 v91, v101, 0, s[10:11]
	v_cndmask_b32_e64 v90, v96, 0, s[10:11]
	v_cndmask_b32_e64 v93, v105, 0, s[10:11]
	v_cndmask_b32_e64 v92, v103, 0, s[10:11]
	v_cndmask_b32_e64 v77, v77, v106, s[12:13]
	v_cndmask_b32_e64 v76, v76, v104, s[12:13]
	v_cndmask_b32_e64 v79, v79, v102, s[12:13]
	v_cndmask_b32_e64 v78, v78, v100, s[12:13]
	v_mov_b32_dpp v107, v52 row_ror:1 row_mask:0xf bank_mask:0xf
	v_mov_b32_dpp v109, v53 row_ror:1 row_mask:0xf bank_mask:0xf
	v_mov_b32_dpp v111, v54 row_ror:1 row_mask:0xf bank_mask:0xf
	v_mov_b32_dpp v113, v55 row_ror:1 row_mask:0xf bank_mask:0xf
	v_mov_b32_dpp v108, v48 row_ror:15 row_mask:0xf bank_mask:0xf
	v_mov_b32_dpp v110, v49 row_ror:15 row_mask:0xf bank_mask:0xf
	v_mov_b32_dpp v112, v50 row_ror:15 row_mask:0xf bank_mask:0xf
	v_mov_b32_dpp v114, v51 row_ror:15 row_mask:0xf bank_mask:0xf
	s_waitcnt vmcnt(3)
	v_pk_mul_f32 v[92:93], v[62:63], v[92:93]
	v_pk_mul_f32 v[90:91], v[60:61], v[90:91]
	s_waitcnt vmcnt(2)
	v_pk_fma_f32 v[92:93], v[38:39], v[58:59], v[92:93]
	s_waitcnt vmcnt(0)
	v_pk_fma_f32 v[78:79], v[64:65], v[78:79], v[68:69]
	v_pk_fma_f32 v[76:77], v[66:67], v[76:77], v[70:71]
	v_pk_fma_f32 v[90:91], v[36:37], v[56:57], v[90:91]
	v_pk_add_f32 v[76:77], v[92:93], v[76:77]
	v_pk_add_f32 v[78:79], v[90:91], v[78:79]
	v_mul_f32_e32 v92, 0xbfb8aa3b, v76
	v_mul_f32_e32 v90, 0xbfb8aa3b, v78
	v_mul_f32_e32 v91, 0xbfb8aa3b, v79
	v_mul_f32_e32 v93, 0xbfb8aa3b, v77
	v_exp_f32_e32 v90, v90
	v_exp_f32_e32 v91, v91
	v_exp_f32_e32 v92, v92
	v_exp_f32_e32 v93, v93
	v_add_f32_e32 v90, 1.0, v90
	v_add_f32_e32 v91, 1.0, v91
	v_add_f32_e32 v92, 1.0, v92
	v_add_f32_e32 v93, 1.0, v93
	v_rcp_f32_e32 v90, v90
	v_rcp_f32_e32 v91, v91
	v_rcp_f32_e32 v92, v92
	v_rcp_f32_e32 v93, v93
	v_pk_mul_f32 v[78:79], v[78:79], v[90:91]
	v_cndmask_b32_e64 v91, v109, v101, s[10:11]
	v_pk_mul_f32 v[76:77], v[76:77], v[92:93]
	v_cndmask_b32_e64 v90, v107, v96, s[10:11]
	v_cndmask_b32_e64 v93, v113, v105, s[10:11]
	v_cndmask_b32_e64 v92, v111, v103, s[10:11]
	v_pk_mul_f32 v[76:77], v[84:85], v[76:77]
	v_pk_mul_f32 v[78:79], v[82:83], v[78:79]
	v_cndmask_b32_e64 v83, v106, v114, s[12:13]
	v_cndmask_b32_e64 v82, v104, v112, s[12:13]
	v_cndmask_b32_e64 v85, v102, v110, s[12:13]
	v_cndmask_b32_e64 v84, v100, v108, s[12:13]
	v_pk_mul_f32 v[92:93], v[62:63], v[92:93]
	v_pk_mul_f32 v[90:91], v[60:61], v[90:91]
	v_pk_fma_f32 v[84:85], v[64:65], v[84:85], v[68:69]
	v_pk_fma_f32 v[82:83], v[66:67], v[82:83], v[70:71]
	v_pk_fma_f32 v[52:53], v[52:53], v[56:57], v[90:91]
	v_pk_fma_f32 v[54:55], v[54:55], v[58:59], v[92:93]
	v_pk_add_f32 v[52:53], v[52:53], v[84:85]
	v_pk_add_f32 v[54:55], v[54:55], v[82:83]
	v_mul_f32_e32 v82, 0xbfb8aa3b, v52
	v_mul_f32_e32 v83, 0xbfb8aa3b, v53
	v_mul_f32_e32 v84, 0xbfb8aa3b, v54
	v_mul_f32_e32 v85, 0xbfb8aa3b, v55
	v_exp_f32_e32 v82, v82
	v_exp_f32_e32 v83, v83
	v_exp_f32_e32 v84, v84
	v_exp_f32_e32 v85, v85
	v_add_f32_e32 v82, 1.0, v82
	v_add_f32_e32 v83, 1.0, v83
	v_add_f32_e32 v84, 1.0, v84
	v_add_f32_e32 v85, 1.0, v85
	v_rcp_f32_e32 v82, v82
	v_rcp_f32_e32 v83, v83
	v_rcp_f32_e32 v84, v84
	v_rcp_f32_e32 v85, v85
	v_mov_b32_e32 v96, v97
	v_pk_mul_f32 v[52:53], v[52:53], v[82:83]
	v_mov_b32_e32 v101, v97
	v_pk_mul_f32 v[54:55], v[54:55], v[84:85]
	v_pk_mul_f32 v[52:53], v[94:95], v[52:53]
	v_pk_mul_f32 v[82:83], v[98:99], v[54:55]
	v_mov_b32_e32 v94, v97
	v_mov_b32_e32 v99, v97
	v_mov_b32_e32 v95, v97
	v_mov_b32_dpp v94, v48 row_ror:1 row_mask:0xf bank_mask:0xf
	v_mov_b32_dpp v96, v49 row_ror:1 row_mask:0xf bank_mask:0xf
	v_mov_b32_e32 v98, v97
	v_mov_b32_dpp v99, v50 row_ror:1 row_mask:0xf bank_mask:0xf
	v_mov_b32_e32 v100, v97
	v_mov_b32_dpp v101, v51 row_ror:1 row_mask:0xf bank_mask:0xf
	v_mov_b32_e32 v102, v97
	v_mov_b32_dpp v95, v32 row_ror:15 row_mask:0xf bank_mask:0xf
	v_mov_b32_dpp v98, v33 row_ror:15 row_mask:0xf bank_mask:0xf
	v_mov_b32_dpp v100, v34 row_ror:15 row_mask:0xf bank_mask:0xf
	v_mov_b32_dpp v102, v35 row_ror:15 row_mask:0xf bank_mask:0xf
	v_cndmask_b32_e64 v91, v96, v109, s[10:11]
	v_cndmask_b32_e64 v90, v94, v107, s[10:11]
	v_cndmask_b32_e64 v93, v101, v113, s[10:11]
	v_cndmask_b32_e64 v92, v99, v111, s[10:11]
	v_cndmask_b32_e64 v55, v114, v102, s[12:13]
	v_cndmask_b32_e64 v54, v112, v100, s[12:13]
	v_cndmask_b32_e64 v85, v110, v98, s[12:13]
	v_cndmask_b32_e64 v84, v108, v95, s[12:13]
	v_pk_mul_f32 v[92:93], v[62:63], v[92:93]
	v_pk_mul_f32 v[90:91], v[60:61], v[90:91]
	v_pk_fma_f32 v[84:85], v[64:65], v[84:85], v[68:69]
	v_pk_fma_f32 v[54:55], v[66:67], v[54:55], v[70:71]
	v_pk_fma_f32 v[48:49], v[48:49], v[56:57], v[90:91]
	v_pk_fma_f32 v[50:51], v[50:51], v[58:59], v[92:93]
; __device__ __forceinline__ unsigned cvt_pk_bf16(float lo, float hi) { unsigned r; asm volatile("v_cvt_pk_bf16_f32 %0, %1, %2" : "=v"(r) : "v"(lo), "v"(hi)); return r; }
;     __device__ __forceinline__ void operator()(const f32x4 (&acc)[2][2][4][2], const Unit& u, int wr, int wc, int fr_in, int fq_in) const {
;     ...
;             for (int n = 0; n < 2; ++n) {
;                 const int ch = ch0 + 4 * n;
; #pragma unroll
;                 for (int pass = 0; pass < 2; ++pass) {
;                     const int co = pass ? DFF : 0;
;                     const f32x4 k0 = *(const f32x4*)(fk + co + ch), k1 = *(const f32x4*)(fk + DFF2 + co + ch), k2 = *(const f32x4*)(fk + 2 * DFF2 + co + ch), bb = *(const f32x4*)(fb + co + ch);
;                     f32x4 up_prev = (f32x4){0.f, 0.f, 0.f, 0.f}, up_cur, dn_cur, dn_next;
; #pragma unroll
;                     for (int j = 0; j < 4; ++j) dn_cur[j] = DPP_DN(acc[ai][pass][0][n][j]);
;     ...
;                         else { f32x4 e;
; #pragma unroll
;                             for (int j = 0; j < 4; ++j) e[j] = __builtin_amdgcn_rcpf(1.0f + __builtin_amdgcn_exp2f(c[j] * -1.4426950408889634f));
;                             o[m] = o[m] * (c * e); }
;                         up_prev = up_cur; dn_cur = dn_next; }
;                 }
;                 if (n == 0) {
; #pragma unroll
;                     for (int m = 0; m < 4; ++m) { wlo[m].x = cvt_pk_bf16(o[m][0], o[m][1]); wlo[m].y = cvt_pk_bf16(o[m][2], o[m][3]); }
;                 } else {
; #pragma unroll
;                     for (int m = 0; m < 4; ++m) { u32x4 w; w.x = wlo[m].x; w.y = wlo[m].y; w.z = cvt_pk_bf16(o[m][0], o[m][1]); w.w = cvt_pk_bf16(o[m][2], o[m][3]);
;                         *(u32x4*)(base + off0 + (unsigned)(ai * HALF + m * 16) * (DFF * 2u)) = w; }
;                 }
;                 if (fr < 2 || fr >= 14) { const int k = fr < 2 ? fr : fr - 12;
;                     const f32x4 xv = fr < 2 ? acc[ai][0][0][n] : acc[ai][0][3][n], yv = fr < 2 ? acc[ai][1][0][n] : acc[ai][1][3][n];
;                     char* sp = sbase + (size_t)((2 * ai + wr) * 4 + k) * (DFF2 * 2) + (size_t)ch * 2;
;                     u32x2 a, b; a.x = cvt_pk_bf16(xv[0], xv[1]); a.y = cvt_pk_bf16(xv[2], xv[3]); b.x = cvt_pk_bf16(yv[0], yv[1]); b.y = cvt_pk_bf16(yv[2], yv[3]);
;                     *(u32x2*)sp = a; *(u32x2*)(sp + DFF * 2) = b; }
	v_pk_add_f32 v[48:49], v[48:49], v[84:85]
	v_pk_add_f32 v[50:51], v[50:51], v[54:55]
	v_mul_f32_e32 v54, 0xbfb8aa3b, v48
	v_mul_f32_e32 v55, 0xbfb8aa3b, v49
	v_mul_f32_e32 v84, 0xbfb8aa3b, v50
	v_mul_f32_e32 v85, 0xbfb8aa3b, v51
	v_exp_f32_e32 v54, v54
	v_exp_f32_e32 v55, v55
	v_exp_f32_e32 v84, v84
	v_exp_f32_e32 v85, v85
	v_add_f32_e32 v54, 1.0, v54
	v_add_f32_e32 v55, 1.0, v55
	v_add_f32_e32 v84, 1.0, v84
	v_add_f32_e32 v85, 1.0, v85
	v_rcp_f32_e32 v54, v54
	v_rcp_f32_e32 v55, v55
	v_rcp_f32_e32 v84, v84
	v_rcp_f32_e32 v85, v85
	v_pk_mul_f32 v[48:49], v[48:49], v[54:55]
	s_nop 0
	v_pk_mul_f32 v[48:49], v[86:87], v[48:49]
	v_pk_mul_f32 v[50:51], v[50:51], v[84:85]
	v_mov_b32_e32 v86, v97
	v_pk_mul_f32 v[84:85], v[88:89], v[50:51]
	v_mov_b32_e32 v87, v97
	v_mov_b32_e32 v88, v97
	v_mov_b32_e32 v89, v97
	v_mov_b32_dpp v86, v32 row_ror:1 row_mask:0xf bank_mask:0xf
	v_mov_b32_dpp v87, v33 row_ror:1 row_mask:0xf bank_mask:0xf
	v_mov_b32_dpp v88, v34 row_ror:1 row_mask:0xf bank_mask:0xf
	v_mov_b32_dpp v89, v35 row_ror:1 row_mask:0xf bank_mask:0xf
	v_cndmask_b32_e64 v51, v102, 0, s[12:13]
	v_cndmask_b32_e64 v50, v100, 0, s[12:13]
	v_cndmask_b32_e64 v55, v98, 0, s[12:13]
	v_cndmask_b32_e64 v54, v95, 0, s[12:13]
	v_pk_fma_f32 v[54:55], v[64:65], v[54:55], v[68:69]
	v_pk_fma_f32 v[50:51], v[66:67], v[50:51], v[70:71]
	v_cndmask_b32_e64 v65, v87, v96, s[10:11]
	v_cndmask_b32_e64 v64, v86, v94, s[10:11]
	v_cndmask_b32_e64 v67, v89, v101, s[10:11]
	v_cndmask_b32_e64 v66, v88, v99, s[10:11]
	v_pk_mul_f32 v[62:63], v[62:63], v[66:67]
	v_pk_mul_f32 v[60:61], v[60:61], v[64:65]
	v_pk_fma_f32 v[58:59], v[34:35], v[58:59], v[62:63]
	v_pk_fma_f32 v[56:57], v[32:33], v[56:57], v[60:61]
	v_pk_add_f32 v[50:51], v[50:51], v[58:59]
	v_pk_add_f32 v[54:55], v[54:55], v[56:57]
	v_mul_f32_e32 v58, 0xbfb8aa3b, v50
	v_mul_f32_e32 v56, 0xbfb8aa3b, v54
	v_mul_f32_e32 v57, 0xbfb8aa3b, v55
	v_mul_f32_e32 v59, 0xbfb8aa3b, v51
	v_exp_f32_e32 v56, v56
	v_exp_f32_e32 v57, v57
	v_exp_f32_e32 v58, v58
	v_exp_f32_e32 v59, v59
	v_add_f32_e32 v56, 1.0, v56
	v_add_f32_e32 v57, 1.0, v57
	v_add_f32_e32 v58, 1.0, v58
	v_add_f32_e32 v59, 1.0, v59
	v_rcp_f32_e32 v56, v56
	v_rcp_f32_e32 v57, v57
	v_rcp_f32_e32 v58, v58
	v_rcp_f32_e32 v59, v59
	v_pk_mul_f32 v[54:55], v[54:55], v[56:57]
	v_pk_mul_f32 v[50:51], v[50:51], v[58:59]
	s_nop 0
	v_pk_mul_f32 v[56:57], v[74:75], v[50:51]
	v_pk_mul_f32 v[58:59], v[72:73], v[54:55]
	v_cvt_pk_bf16_f32 v54, v78, v79
	v_cvt_pk_bf16_f32 v55, v76, v77
	v_cvt_pk_bf16_f32 v52, v52, v53
	v_cvt_pk_bf16_f32 v53, v82, v83
	v_cvt_pk_bf16_f32 v50, v48, v49
	v_cvt_pk_bf16_f32 v51, v84, v85
	s_nop 0
	v_cvt_pk_bf16_f32 v48, v58, v59
	v_cvt_pk_bf16_f32 v49, v56, v57
	s_and_saveexec_b64 s[22:23], s[8:9]
	s_cbranch_execz .LBB0_1052
	v_cndmask_b32_e64 v36, v32, v36, s[6:7]
	v_cndmask_b32_e64 v37, v33, v37, s[6:7]
	v_lshl_add_u64 v[32:33], v[158:159], 1, v[80:81]
	v_cndmask_b32_e64 v42, v42, v46, s[6:7]
	v_cndmask_b32_e64 v43, v43, v47, s[6:7]
	v_cndmask_b32_e64 v40, v40, v44, s[6:7]
	v_cndmask_b32_e64 v41, v41, v45, s[6:7]
	v_cndmask_b32_e64 v38, v34, v38, s[6:7]
	v_cndmask_b32_e64 v39, v35, v39, s[6:7]
	v_cvt_pk_bf16_f32 v34, v40, v41
	v_cvt_pk_bf16_f32 v35, v42, v43
	v_cvt_pk_bf16_f32 v36, v36, v37
	v_cvt_pk_bf16_f32 v37, v38, v39
	global_store_dwordx2 v[32:33], v[34:35], off
	v_add_co_u32_e32 v32, vcc, 0x1000, v32
	s_nop 1
	v_addc_co_u32_e32 v33, vcc, 0, v33, vcc
	global_store_dwordx2 v[32:33], v[36:37], off offset:1536
.LBB0_1052:
	s_or_b64 exec, exec, s[22:23]
	v_lshl_add_u64 v[32:33], v[160:161], 0, 16
	v_lshl_add_u64 v[44:45], v[162:163], 0, 16
	global_load_dwordx4 v[36:39], v[32:33], off
	s_nop 0
	global_load_dwordx4 v[32:35], v[130:131], off
	global_load_dwordx4 v[40:43], v[128:129], off
	s_nop 0
	global_load_dwordx4 v[44:47], v[44:45], off
	v_mov_b32_dpp v76, v2 row_ror:1 row_mask:0xf bank_mask:0xf
	v_mov_b32_dpp v78, v3 row_ror:1 row_mask:0xf bank_mask:0xf
	v_mov_b32_dpp v58, v2 row_ror:15 row_mask:0xf bank_mask:0xf
	v_mov_b32_dpp v59, v3 row_ror:15 row_mask:0xf bank_mask:0xf
	v_mov_b32_dpp v70, v0 row_ror:1 row_mask:0xf bank_mask:0xf
	v_mov_b32_dpp v71, v1 row_ror:1 row_mask:0xf bank_mask:0xf
	v_mov_b32_dpp v77, v30 row_ror:15 row_mask:0xf bank_mask:0xf
	v_mov_b32_dpp v79, v31 row_ror:15 row_mask:0xf bank_mask:0xf
	v_cndmask_b32_e64 v61, v78, 0, s[10:11]
	v_cndmask_b32_e64 v60, v76, 0, s[10:11]
	v_mov_b32_dpp v56, v0 row_ror:15 row_mask:0xf bank_mask:0xf
	v_mov_b32_dpp v57, v1 row_ror:15 row_mask:0xf bank_mask:0xf
	v_mov_b32_dpp v68, v28 row_ror:15 row_mask:0xf bank_mask:0xf
	v_mov_b32_dpp v69, v29 row_ror:15 row_mask:0xf bank_mask:0xf
	v_cndmask_b32_e64 v59, v59, v79, s[12:13]
	v_cndmask_b32_e64 v58, v58, v77, s[12:13]
	v_cndmask_b32_e64 v63, v71, 0, s[10:11]
	v_cndmask_b32_e64 v62, v70, 0, s[10:11]
	v_cndmask_b32_e64 v57, v57, v69, s[12:13]
	v_cndmask_b32_e64 v56, v56, v68, s[12:13]
	v_mov_b32_dpp v82, v28 row_ror:1 row_mask:0xf bank_mask:0xf
	v_mov_b32_dpp v83, v24 row_ror:15 row_mask:0xf bank_mask:0xf
	v_mov_b32_dpp v84, v29 row_ror:1 row_mask:0xf bank_mask:0xf
	v_mov_b32_dpp v85, v25 row_ror:15 row_mask:0xf bank_mask:0xf
	v_mov_b32_dpp v86, v30 row_ror:1 row_mask:0xf bank_mask:0xf
	v_mov_b32_e32 v87, v97
	v_mov_b32_dpp v88, v31 row_ror:1 row_mask:0xf bank_mask:0xf
	v_mov_b32_e32 v89, v97
	v_mov_b32_dpp v87, v26 row_ror:15 row_mask:0xf bank_mask:0xf
	v_cndmask_b32_e64 v71, v84, v71, s[10:11]
	v_mov_b32_dpp v89, v27 row_ror:15 row_mask:0xf bank_mask:0xf
	v_cndmask_b32_e64 v70, v82, v70, s[10:11]
	v_mov_b32_dpp v90, v26 row_ror:1 row_mask:0xf bank_mask:0xf
	v_mov_b32_dpp v92, v27 row_ror:1 row_mask:0xf bank_mask:0xf
	v_mov_b32_dpp v91, v6 row_ror:15 row_mask:0xf bank_mask:0xf
	s_mov_b64 s[22:23], 0x2c10
	v_mov_b32_dpp v93, v7 row_ror:15 row_mask:0xf bank_mask:0xf
	v_lshl_add_u64 v[72:73], v[160:161], 0, s[22:23]
	s_mov_b64 s[0:1], 0x2c00
	v_lshl_add_u64 v[74:75], v[130:131], 0, s[0:1]
	v_lshl_add_u64 v[64:65], v[128:129], 0, s[0:1]
	v_lshl_add_u64 v[66:67], v[162:163], 0, s[22:23]
	s_mov_b32 s0, 0xb0000
	s_waitcnt vmcnt(3)
; #define DPP_UP(v) __int_as_float(__builtin_amdgcn_update_dpp(0, __float_as_int(v), 0x121, 0xf, 0xf, false))
; #define DPP_DN(v) __int_as_float(__builtin_amdgcn_update_dpp(0, __float_as_int(v), 0x12F, 0xf, 0xf, false))
;     __device__ __forceinline__ void operator()(const f32x4 (&acc)[2][2][4][2], const Unit& u, int wr, int wc, int fr_in, int fq_in) const {
;     ...
;                 for (int pass = 0; pass < 2; ++pass) {
;                     const int co = pass ? DFF : 0;
;                     const f32x4 k0 = *(const f32x4*)(fk + co + ch), k1 = *(const f32x4*)(fk + DFF2 + co + ch), k2 = *(const f32x4*)(fk + 2 * DFF2 + co + ch), bb = *(const f32x4*)(fb + co + ch);
;                     f32x4 up_prev = (f32x4){0.f, 0.f, 0.f, 0.f}, up_cur, dn_cur, dn_next;
; #pragma unroll
;                     for (int j = 0; j < 4; ++j) dn_cur[j] = DPP_DN(acc[ai][pass][0][n][j]);
; #pragma unroll
;                     for (int m = 0; m < 4; ++m) {
;                         const f32x4 xv = acc[ai][pass][m][n];
; #pragma unroll
;                         for (int j = 0; j < 4; ++j) { up_cur[j] = DPP_UP(xv[j]); dn_next[j] = (m < 3) ? DPP_DN(acc[ai][pass][m < 3 ? m + 1 : 3][n][j]) : 0.f; }
;                         const f32x4 xp = f0 ? up_prev : up_cur, xn = f15 ? dn_next : dn_cur;
;                         const f32x4 c = (k0 * xp + k1 * xv) + (k2 * xn + bb);
;                         if (pass == 0) o[m] = c;
;                         else { f32x4 e;
; #pragma unroll
;                             for (int j = 0; j < 4; ++j) e[j] = __builtin_amdgcn_rcpf(1.0f + __builtin_amdgcn_exp2f(c[j] * -1.4426950408889634f));
;                             o[m] = o[m] * (c * e); }
;                         up_prev = up_cur; dn_cur = dn_next; }
	v_pk_mul_f32 v[60:61], v[38:39], v[60:61]
	v_pk_mul_f32 v[62:63], v[36:37], v[62:63]
	s_waitcnt vmcnt(2)
	v_pk_fma_f32 v[60:61], v[2:3], v[34:35], v[60:61]
	s_waitcnt vmcnt(0)
	v_pk_fma_f32 v[58:59], v[42:43], v[58:59], v[46:47]
	v_pk_fma_f32 v[56:57], v[40:41], v[56:57], v[44:45]
	v_pk_fma_f32 v[62:63], v[0:1], v[32:33], v[62:63]
	v_pk_add_f32 v[58:59], v[60:61], v[58:59]
	v_cndmask_b32_e64 v61, v69, v85, s[12:13]
	v_cndmask_b32_e64 v60, v68, v83, s[12:13]
	v_cndmask_b32_e64 v69, v88, v78, s[10:11]
	v_cndmask_b32_e64 v68, v86, v76, s[10:11]
	v_mov_b32_e32 v76, v97
	v_mov_b32_e32 v78, v97
	v_pk_add_f32 v[56:57], v[62:63], v[56:57]
	v_cndmask_b32_e64 v63, v79, v89, s[12:13]
	v_cndmask_b32_e64 v62, v77, v87, s[12:13]
	v_pk_mul_f32 v[70:71], v[36:37], v[70:71]
	v_pk_mul_f32 v[68:69], v[38:39], v[68:69]
	v_mov_b32_dpp v76, v24 row_ror:1 row_mask:0xf bank_mask:0xf
	v_mov_b32_e32 v77, v97
	v_mov_b32_dpp v78, v25 row_ror:1 row_mask:0xf bank_mask:0xf
	v_mov_b32_e32 v79, v97
	v_pk_fma_f32 v[62:63], v[42:43], v[62:63], v[46:47]
	v_pk_fma_f32 v[60:61], v[40:41], v[60:61], v[44:45]
	v_pk_fma_f32 v[30:31], v[30:31], v[34:35], v[68:69]
	v_pk_fma_f32 v[28:29], v[28:29], v[32:33], v[70:71]
	v_mov_b32_dpp v77, v4 row_ror:15 row_mask:0xf bank_mask:0xf
	v_mov_b32_dpp v79, v5 row_ror:15 row_mask:0xf bank_mask:0xf
	v_cndmask_b32_e64 v69, v92, v88, s[10:11]
	v_cndmask_b32_e64 v68, v90, v86, s[10:11]
	v_cndmask_b32_e64 v71, v78, v84, s[10:11]
	v_cndmask_b32_e64 v70, v76, v82, s[10:11]
	v_pk_add_f32 v[60:61], v[28:29], v[60:61]
	v_pk_add_f32 v[62:63], v[30:31], v[62:63]
	v_cndmask_b32_e64 v29, v85, v79, s[12:13]
	v_cndmask_b32_e64 v28, v83, v77, s[12:13]
	v_cndmask_b32_e64 v31, v89, v93, s[12:13]
	v_cndmask_b32_e64 v30, v87, v91, s[12:13]
	v_pk_mul_f32 v[70:71], v[36:37], v[70:71]
	v_pk_mul_f32 v[68:69], v[38:39], v[68:69]
	v_pk_fma_f32 v[30:31], v[42:43], v[30:31], v[46:47]
	v_pk_fma_f32 v[28:29], v[40:41], v[28:29], v[44:45]
	v_pk_fma_f32 v[26:27], v[26:27], v[34:35], v[68:69]
	v_pk_fma_f32 v[24:25], v[24:25], v[32:33], v[70:71]
	v_pk_add_f32 v[70:71], v[26:27], v[30:31]
	v_pk_add_f32 v[68:69], v[24:25], v[28:29]
	v_mov_b32_e32 v30, v97
	v_mov_b32_e32 v31, v97
	v_mov_b32_e32 v28, v97
	v_mov_b32_e32 v29, v97
	v_mov_b32_dpp v30, v4 row_ror:1 row_mask:0xf bank_mask:0xf
	v_mov_b32_dpp v31, v5 row_ror:1 row_mask:0xf bank_mask:0xf
	v_mov_b32_dpp v28, v6 row_ror:1 row_mask:0xf bank_mask:0xf
	v_mov_b32_dpp v29, v7 row_ror:1 row_mask:0xf bank_mask:0xf
	v_cndmask_b32_e64 v29, v29, v92, s[10:11]
	v_cndmask_b32_e64 v28, v28, v90, s[10:11]
	v_cndmask_b32_e64 v31, v31, v78, s[10:11]
	v_cndmask_b32_e64 v30, v30, v76, s[10:11]
	v_cndmask_b32_e64 v25, v79, 0, s[12:13]
	v_cndmask_b32_e64 v24, v77, 0, s[12:13]
	v_cndmask_b32_e64 v27, v93, 0, s[12:13]
	v_cndmask_b32_e64 v26, v91, 0, s[12:13]
	v_pk_mul_f32 v[30:31], v[36:37], v[30:31]
	v_pk_mul_f32 v[28:29], v[38:39], v[28:29]
	v_pk_fma_f32 v[26:27], v[42:43], v[26:27], v[46:47]
	v_pk_fma_f32 v[24:25], v[40:41], v[24:25], v[44:45]
	v_pk_fma_f32 v[28:29], v[6:7], v[34:35], v[28:29]
	v_pk_fma_f32 v[30:31], v[4:5], v[32:33], v[30:31]
	v_pk_add_f32 v[42:43], v[26:27], v[28:29]
	v_pk_add_f32 v[40:41], v[24:25], v[30:31]
	global_load_dwordx4 v[28:31], v[72:73], off
	global_load_dwordx4 v[24:27], v[74:75], off
	global_load_dwordx4 v[32:35], v[64:65], off
	global_load_dwordx4 v[36:39], v[66:67], off
	v_mov_b32_dpp v72, v8 row_ror:1 row_mask:0xf bank_mask:0xf
	v_mov_b32_dpp v74, v9 row_ror:1 row_mask:0xf bank_mask:0xf
	v_mov_b32_dpp v76, v10 row_ror:1 row_mask:0xf bank_mask:0xf
	v_mov_b32_dpp v78, v11 row_ror:1 row_mask:0xf bank_mask:0xf
	v_mov_b32_dpp v46, v8 row_ror:15 row_mask:0xf bank_mask:0xf
	v_mov_b32_dpp v47, v9 row_ror:15 row_mask:0xf bank_mask:0xf
	v_mov_b32_dpp v44, v10 row_ror:15 row_mask:0xf bank_mask:0xf
	v_mov_b32_dpp v45, v11 row_ror:15 row_mask:0xf bank_mask:0xf
	v_mov_b32_dpp v73, v20 row_ror:15 row_mask:0xf bank_mask:0xf
	v_mov_b32_dpp v75, v21 row_ror:15 row_mask:0xf bank_mask:0xf
	v_mov_b32_dpp v77, v22 row_ror:15 row_mask:0xf bank_mask:0xf
	v_mov_b32_dpp v79, v23 row_ror:15 row_mask:0xf bank_mask:0xf
	v_cndmask_b32_e64 v65, v74, 0, s[10:11]
	v_cndmask_b32_e64 v64, v72, 0, s[10:11]
	v_cndmask_b32_e64 v67, v78, 0, s[10:11]
	v_cndmask_b32_e64 v66, v76, 0, s[10:11]
	v_cndmask_b32_e64 v45, v45, v79, s[12:13]
	v_cndmask_b32_e64 v44, v44, v77, s[12:13]
	v_cndmask_b32_e64 v47, v47, v75, s[12:13]
	v_cndmask_b32_e64 v46, v46, v73, s[12:13]
	v_mov_b32_dpp v82, v20 row_ror:1 row_mask:0xf bank_mask:0xf
	v_mov_b32_dpp v84, v21 row_ror:1 row_mask:0xf bank_mask:0xf
	v_mov_b32_dpp v86, v22 row_ror:1 row_mask:0xf bank_mask:0xf
	v_mov_b32_dpp v88, v23 row_ror:1 row_mask:0xf bank_mask:0xf
	v_mov_b32_dpp v83, v16 row_ror:15 row_mask:0xf bank_mask:0xf
	v_mov_b32_dpp v85, v17 row_ror:15 row_mask:0xf bank_mask:0xf
	v_mov_b32_dpp v87, v18 row_ror:15 row_mask:0xf bank_mask:0xf
	v_mov_b32_dpp v89, v19 row_ror:15 row_mask:0xf bank_mask:0xf
	s_waitcnt vmcnt(3)
	v_pk_mul_f32 v[66:67], v[30:31], v[66:67]
	v_pk_mul_f32 v[64:65], v[28:29], v[64:65]
	s_waitcnt vmcnt(2)
	v_pk_fma_f32 v[66:67], v[10:11], v[26:27], v[66:67]
	s_waitcnt vmcnt(0)
; __device__ __forceinline__ unsigned cvt_pk_bf16(float lo, float hi) { unsigned r; asm volatile("v_cvt_pk_bf16_f32 %0, %1, %2" : "=v"(r) : "v"(lo), "v"(hi)); return r; }
;     __device__ __forceinline__ void operator()(const f32x4 (&acc)[2][2][4][2], const Unit& u, int wr, int wc, int fr_in, int fq_in) const {
;     ...
;                         else { f32x4 e;
; #pragma unroll
;                             for (int j = 0; j < 4; ++j) e[j] = __builtin_amdgcn_rcpf(1.0f + __builtin_amdgcn_exp2f(c[j] * -1.4426950408889634f));
;                             o[m] = o[m] * (c * e); }
;                         up_prev = up_cur; dn_cur = dn_next; }
;                 }
;                 if (n == 0) {
; #pragma unroll
;                     for (int m = 0; m < 4; ++m) { wlo[m].x = cvt_pk_bf16(o[m][0], o[m][1]); wlo[m].y = cvt_pk_bf16(o[m][2], o[m][3]); }
;                 } else {
; #pragma unroll
;                     for (int m = 0; m < 4; ++m) { u32x4 w; w.x = wlo[m].x; w.y = wlo[m].y; w.z = cvt_pk_bf16(o[m][0], o[m][1]); w.w = cvt_pk_bf16(o[m][2], o[m][3]);
;                         *(u32x4*)(base + off0 + (unsigned)(ai * HALF + m * 16) * (DFF * 2u)) = w; }
	v_pk_fma_f32 v[46:47], v[32:33], v[46:47], v[36:37]
	v_pk_fma_f32 v[44:45], v[34:35], v[44:45], v[38:39]
	v_pk_fma_f32 v[64:65], v[8:9], v[24:25], v[64:65]
	v_pk_add_f32 v[44:45], v[66:67], v[44:45]
	v_pk_add_f32 v[46:47], v[64:65], v[46:47]
	v_mul_f32_e32 v66, 0xbfb8aa3b, v44
	v_mul_f32_e32 v64, 0xbfb8aa3b, v46
	v_mul_f32_e32 v65, 0xbfb8aa3b, v47
	v_mul_f32_e32 v67, 0xbfb8aa3b, v45
	v_exp_f32_e32 v64, v64
	v_exp_f32_e32 v65, v65
	v_exp_f32_e32 v66, v66
	v_exp_f32_e32 v67, v67
	v_add_f32_e32 v64, 1.0, v64
	v_add_f32_e32 v65, 1.0, v65
	v_add_f32_e32 v66, 1.0, v66
	v_add_f32_e32 v67, 1.0, v67
	v_rcp_f32_e32 v64, v64
	v_rcp_f32_e32 v65, v65
	v_rcp_f32_e32 v66, v66
	v_rcp_f32_e32 v67, v67
	v_pk_mul_f32 v[46:47], v[46:47], v[64:65]
	v_cndmask_b32_e64 v65, v84, v74, s[10:11]
	v_pk_mul_f32 v[44:45], v[44:45], v[66:67]
	v_cndmask_b32_e64 v64, v82, v72, s[10:11]
	v_cndmask_b32_e64 v67, v88, v78, s[10:11]
	v_cndmask_b32_e64 v66, v86, v76, s[10:11]
	v_pk_mul_f32 v[44:45], v[58:59], v[44:45]
	v_pk_mul_f32 v[46:47], v[56:57], v[46:47]
	v_cndmask_b32_e64 v57, v79, v89, s[12:13]
	v_cndmask_b32_e64 v56, v77, v87, s[12:13]
	v_cndmask_b32_e64 v59, v75, v85, s[12:13]
	v_cndmask_b32_e64 v58, v73, v83, s[12:13]
	v_pk_mul_f32 v[66:67], v[30:31], v[66:67]
	v_pk_mul_f32 v[64:65], v[28:29], v[64:65]
	v_pk_fma_f32 v[58:59], v[32:33], v[58:59], v[36:37]
	v_pk_fma_f32 v[56:57], v[34:35], v[56:57], v[38:39]
	v_pk_fma_f32 v[20:21], v[20:21], v[24:25], v[64:65]
	v_pk_fma_f32 v[22:23], v[22:23], v[26:27], v[66:67]
	v_pk_add_f32 v[20:21], v[20:21], v[58:59]
	v_pk_add_f32 v[22:23], v[22:23], v[56:57]
	v_mul_f32_e32 v56, 0xbfb8aa3b, v20
	v_mul_f32_e32 v57, 0xbfb8aa3b, v21
	v_mul_f32_e32 v58, 0xbfb8aa3b, v22
	v_mul_f32_e32 v59, 0xbfb8aa3b, v23
	v_exp_f32_e32 v56, v56
	v_exp_f32_e32 v57, v57
	v_exp_f32_e32 v58, v58
	v_exp_f32_e32 v59, v59
	v_add_f32_e32 v56, 1.0, v56
	v_add_f32_e32 v57, 1.0, v57
	v_add_f32_e32 v58, 1.0, v58
	v_add_f32_e32 v59, 1.0, v59
	v_rcp_f32_e32 v56, v56
	v_rcp_f32_e32 v57, v57
	v_rcp_f32_e32 v58, v58
	v_rcp_f32_e32 v59, v59
	v_mov_b32_e32 v72, v97
	v_mov_b32_e32 v74, v97
	v_pk_mul_f32 v[56:57], v[20:21], v[56:57]
	v_pk_mul_f32 v[20:21], v[22:23], v[58:59]
	v_mov_b32_e32 v64, v97
	v_mov_b32_e32 v66, v97
	v_mov_b32_dpp v72, v18 row_ror:1 row_mask:0xf bank_mask:0xf
	v_mov_b32_e32 v73, v97
	v_mov_b32_dpp v74, v19 row_ror:1 row_mask:0xf bank_mask:0xf
	v_mov_b32_e32 v75, v97
	v_pk_mul_f32 v[20:21], v[62:63], v[20:21]
	v_mov_b32_dpp v64, v16 row_ror:1 row_mask:0xf bank_mask:0xf
	v_mov_b32_e32 v65, v97
	v_mov_b32_dpp v66, v17 row_ror:1 row_mask:0xf bank_mask:0xf
	v_mov_b32_e32 v67, v97
	v_mov_b32_dpp v73, v14 row_ror:15 row_mask:0xf bank_mask:0xf
	v_mov_b32_dpp v75, v15 row_ror:15 row_mask:0xf bank_mask:0xf
	v_cndmask_b32_e64 v63, v74, v88, s[10:11]
	v_cndmask_b32_e64 v62, v72, v86, s[10:11]
	v_pk_mul_f32 v[22:23], v[60:61], v[56:57]
	v_mov_b32_dpp v65, v12 row_ror:15 row_mask:0xf bank_mask:0xf
	v_mov_b32_dpp v67, v13 row_ror:15 row_mask:0xf bank_mask:0xf
	v_cndmask_b32_e64 v57, v89, v75, s[12:13]
	v_cndmask_b32_e64 v56, v87, v73, s[12:13]
	v_cndmask_b32_e64 v61, v66, v84, s[10:11]
	v_cndmask_b32_e64 v60, v64, v82, s[10:11]
	v_pk_mul_f32 v[62:63], v[30:31], v[62:63]
	v_cndmask_b32_e64 v59, v85, v67, s[12:13]
	v_cndmask_b32_e64 v58, v83, v65, s[12:13]
	v_pk_fma_f32 v[56:57], v[34:35], v[56:57], v[38:39]
	v_pk_mul_f32 v[60:61], v[28:29], v[60:61]
	v_pk_fma_f32 v[18:19], v[18:19], v[26:27], v[62:63]
	v_pk_fma_f32 v[58:59], v[32:33], v[58:59], v[36:37]
	v_pk_fma_f32 v[16:17], v[16:17], v[24:25], v[60:61]
	v_pk_add_f32 v[18:19], v[18:19], v[56:57]
	v_pk_add_f32 v[16:17], v[16:17], v[58:59]
	v_mul_f32_e32 v58, 0xbfb8aa3b, v18
	v_mul_f32_e32 v59, 0xbfb8aa3b, v19
	v_exp_f32_e32 v58, v58
	v_exp_f32_e32 v59, v59
	v_mul_f32_e32 v56, 0xbfb8aa3b, v16
	v_mul_f32_e32 v57, 0xbfb8aa3b, v17
	v_add_f32_e32 v58, 1.0, v58
	v_add_f32_e32 v59, 1.0, v59
	v_rcp_f32_e32 v58, v58
	v_rcp_f32_e32 v59, v59
	v_exp_f32_e32 v56, v56
	v_exp_f32_e32 v57, v57
	v_mov_b32_e32 v60, v97
	v_mov_b32_e32 v61, v97
	v_pk_mul_f32 v[18:19], v[18:19], v[58:59]
	v_mov_b32_dpp v60, v12 row_ror:1 row_mask:0xf bank_mask:0xf
	v_mov_b32_dpp v61, v13 row_ror:1 row_mask:0xf bank_mask:0xf
	v_cndmask_b32_e64 v59, v67, 0, s[12:13]
	v_cndmask_b32_e64 v58, v65, 0, s[12:13]
	v_pk_fma_f32 v[32:33], v[32:33], v[58:59], v[36:37]
	v_cndmask_b32_e64 v37, v61, v66, s[10:11]
	v_cndmask_b32_e64 v36, v60, v64, s[10:11]
	v_add_f32_e32 v56, 1.0, v56
	v_add_f32_e32 v57, 1.0, v57
	v_pk_mul_f32 v[28:29], v[28:29], v[36:37]
	v_rcp_f32_e32 v56, v56
	v_rcp_f32_e32 v57, v57
	v_pk_fma_f32 v[24:25], v[12:13], v[24:25], v[28:29]
	v_mov_b32_e32 v62, v97
	v_pk_add_f32 v[24:25], v[32:33], v[24:25]
	v_mov_b32_e32 v63, v97
	v_mul_f32_e32 v28, 0xbfb8aa3b, v24
	v_mul_f32_e32 v29, 0xbfb8aa3b, v25
	v_exp_f32_e32 v28, v28
	v_exp_f32_e32 v29, v29
	v_pk_mul_f32 v[16:17], v[16:17], v[56:57]
	v_mov_b32_dpp v62, v14 row_ror:1 row_mask:0xf bank_mask:0xf
	v_mov_b32_dpp v63, v15 row_ror:1 row_mask:0xf bank_mask:0xf
	v_cndmask_b32_e64 v57, v75, 0, s[12:13]
	v_cndmask_b32_e64 v56, v73, 0, s[12:13]
	v_pk_fma_f32 v[34:35], v[34:35], v[56:57], v[38:39]
	v_cndmask_b32_e64 v39, v63, v74, s[10:11]
	v_cndmask_b32_e64 v38, v62, v72, s[10:11]
	v_pk_mul_f32 v[30:31], v[30:31], v[38:39]
	v_add_f32_e32 v28, 1.0, v28
	v_pk_fma_f32 v[26:27], v[14:15], v[26:27], v[30:31]
	v_add_f32_e32 v29, 1.0, v29
	v_pk_add_f32 v[26:27], v[34:35], v[26:27]
	v_rcp_f32_e32 v28, v28
	v_rcp_f32_e32 v29, v29
	v_mul_f32_e32 v30, 0xbfb8aa3b, v26
	v_mul_f32_e32 v31, 0xbfb8aa3b, v27
	v_exp_f32_e32 v30, v30
	v_exp_f32_e32 v31, v31
	v_pk_mul_f32 v[24:25], v[24:25], v[28:29]
	v_add_co_u32_e32 v28, vcc, s0, v124
	s_mov_b32 s0, 0xc6000
	s_nop 0
	v_addc_co_u32_e32 v29, vcc, 0, v125, vcc
	v_add_f32_e32 v30, 1.0, v30
	v_add_f32_e32 v31, 1.0, v31
	v_cvt_pk_bf16_f32 v56, v46, v47
	v_cvt_pk_bf16_f32 v57, v44, v45
	global_store_dwordx4 v[28:29], v[54:57], off
	v_pk_mul_f32 v[16:17], v[68:69], v[16:17]
	v_rcp_f32_e32 v30, v30
	v_cvt_pk_bf16_f32 v54, v22, v23
	v_cvt_pk_bf16_f32 v55, v20, v21
	v_add_co_u32_e32 v20, vcc, s0, v124
	v_rcp_f32_e32 v31, v31
	s_nop 0
	v_addc_co_u32_e32 v21, vcc, 0, v125, vcc
	s_mov_b32 s0, 0xdc000
	global_store_dwordx4 v[20:21], v[52:55], off
	v_pk_mul_f32 v[18:19], v[70:71], v[18:19]
	v_pk_mul_f32 v[26:27], v[26:27], v[30:31]
	v_cvt_pk_bf16_f32 v52, v16, v17
	v_add_co_u32_e32 v16, vcc, s0, v124
	v_cvt_pk_bf16_f32 v53, v18, v19
	v_pk_mul_f32 v[26:27], v[42:43], v[26:27]
	s_nop 0
	v_addc_co_u32_e32 v17, vcc, 0, v125, vcc
	global_store_dwordx4 v[16:17], v[50:53], off
	v_add_co_u32_e32 v16, vcc, 0xf2000, v124
	v_pk_mul_f32 v[24:25], v[40:41], v[24:25]
	s_nop 0
	v_addc_co_u32_e32 v17, vcc, 0, v125, vcc
	v_cvt_pk_bf16_f32 v50, v24, v25
	v_cvt_pk_bf16_f32 v51, v26, v27
	global_store_dwordx4 v[16:17], v[48:51], off
	s_and_saveexec_b64 s[10:11], s[8:9]
	s_cbranch_execz .LBB0_1054
; __device__ __forceinline__ unsigned cvt_pk_bf16(float lo, float hi) { unsigned r; asm volatile("v_cvt_pk_bf16_f32 %0, %1, %2" : "=v"(r) : "v"(lo), "v"(hi)); return r; }
;     __device__ __forceinline__ void operator()(const f32x4 (&acc)[2][2][4][2], const Unit& u, int wr, int wc, int fr_in, int fq_in) const {
;     ...
;                 if (fr < 2 || fr >= 14) { const int k = fr < 2 ? fr : fr - 12;
;                     const f32x4 xv = fr < 2 ? acc[ai][0][0][n] : acc[ai][0][3][n], yv = fr < 2 ? acc[ai][1][0][n] : acc[ai][1][3][n];
;                     char* sp = sbase + (size_t)((2 * ai + wr) * 4 + k) * (DFF2 * 2) + (size_t)ch * 2;
;                     u32x2 a, b; a.x = cvt_pk_bf16(xv[0], xv[1]); a.y = cvt_pk_bf16(xv[2], xv[3]); b.x = cvt_pk_bf16(yv[0], yv[1]); b.y = cvt_pk_bf16(yv[2], yv[3]);
;                     *(u32x2*)sp = a; *(u32x2*)(sp + DFF * 2) = b; }
	v_cndmask_b32_e64 v6, v6, v2, s[6:7]
	v_cndmask_b32_e64 v3, v7, v3, s[6:7]
	v_cndmask_b32_e64 v2, v4, v0, s[6:7]
	v_cndmask_b32_e64 v4, v5, v1, s[6:7]
	v_cndmask_b32_e64 v5, v14, v10, s[6:7]
	v_lshl_add_u64 v[0:1], v[126:127], 1, v[80:81]
	v_cndmask_b32_e64 v7, v15, v11, s[6:7]
	v_cndmask_b32_e64 v8, v12, v8, s[6:7]
	v_cndmask_b32_e64 v9, v13, v9, s[6:7]
	v_cvt_pk_bf16_f32 v2, v2, v4
	v_cvt_pk_bf16_f32 v3, v6, v3
	v_cvt_pk_bf16_f32 v4, v8, v9
	v_cvt_pk_bf16_f32 v5, v5, v7
	global_store_dwordx2 v[0:1], v[2:3], off
	v_add_co_u32_e32 v0, vcc, 0x1000, v0
	s_nop 1
	v_addc_co_u32_e32 v1, vcc, 0, v1, vcc
	global_store_dwordx2 v[0:1], v[4:5], off offset:1536
